# XLG: cross-attention LDS waits counted (QK loop keeps the newest fragment read in flight; PV loop reads V fragments through a 4-deep register ring), on top of v070
# speedup vs baseline: 1.0012x; 1.0012x over previous
.LBB0_247:
	s_ashr_i32 s0, s2, 4
	s_lshl_b32 s38, s0, 2
	s_add_i32 s1, s21, s48
	s_add_i32 s22, s1, s38
	s_ashr_i32 s23, s22, 31
	s_lshl_b64 s[22:23], s[22:23], 2
	v_readlane_b32 s28, v249, 1
	v_readlane_b32 s29, v249, 2
	s_add_u32 s22, s28, s22
	s_addc_u32 s23, s29, s23
	s_ashr_i32 s1, s0, 31
	s_lshl_b32 s16, s2, 8
	global_load_dword v201, v0, s[22:23]
	s_and_b32 s16, s16, 0xf00
	s_lshl_b64 s[22:23], s[0:1], 23
	v_readlane_b32 s28, v243, 5
	v_lshl_add_u64 v[2:3], v[178:179], 0, s[16:17]
	s_add_u32 s0, s20, s22
	v_readlane_b32 s29, v243, 6
	v_lshlrev_b64 v[194:195], 11, v[2:3]
	s_addc_u32 s1, s29, s23
	v_lshl_add_u64 v[2:3], s[0:1], 0, v[194:195]
	s_lshl_b32 s0, s21, 8
	s_ashr_i32 s1, s0, 31
	s_lshl_b64 s[28:29], s[0:1], 1
	v_lshl_add_u64 v[2:3], v[2:3], 0, s[28:29]
	v_mov_b32_e32 v189, v0
	v_lshl_add_u64 v[42:43], v[2:3], 0, v[188:189]
	s_barrier
	global_load_dwordx4 v[2:5], v[42:43], off
	global_load_dwordx4 v[6:9], v[42:43], off offset:16
	global_load_dwordx4 v[10:13], v[42:43], off offset:32
	global_load_dwordx4 v[14:17], v[42:43], off offset:48
	s_add_i32 s0, s38, s21
	s_ashr_i32 s1, s0, 31
	s_lshl_b64 s[38:39], s[0:1], 17
	s_add_u32 s40, s34, s38
	v_readfirstlane_b32 s16, v196
	v_add_u32_e32 v167, 0x400, v196
	s_addc_u32 s41, s35, s39
	v_add_u32_e32 v200, 0x4000, v196
	v_readfirstlane_b32 s42, v167
	v_lshl_add_u64 v[44:45], s[40:41], 0, v[190:191]
	s_add_u32 s0, s40, 0x4000
	s_mov_b32 m0, s16
	s_mov_b64 s[58:59], 0x400
	v_add_u32_e32 v199, 0x4400, v196
	global_load_dwordx4 v[18:21], v[42:43], off offset:64
	global_load_dwordx4 v[22:25], v[42:43], off offset:80
	v_readfirstlane_b32 s43, v200
	global_load_dwordx4 v[26:29], v[42:43], off offset:112
	global_load_dwordx4 v[30:33], v[42:43], off offset:96
	global_load_dwordx4 v[34:37], v[42:43], off offset:176
	global_load_dwordx4 v[38:41], v[42:43], off offset:160
	global_load_dwordx4 v[48:51], v[42:43], off offset:144
	global_load_dwordx4 v[60:63], v[42:43], off offset:128
	s_addc_u32 s1, s41, 0
	global_load_lds_dwordx4 v[44:45], off
	v_lshl_add_u64 v[44:45], v[44:45], 0, s[58:59]
	s_mov_b32 m0, s42
	v_add_u32_e32 v197, 0x8000, v196
	v_readfirstlane_b32 s54, v199
	global_load_lds_dwordx4 v[44:45], off
	v_lshl_add_u64 v[44:45], s[0:1], 0, v[190:191]
	v_lshl_add_u64 v[46:47], s[0:1], 0, v[192:193]
	s_add_u32 s0, s40, 0x8000
	s_mov_b32 m0, s43
	v_add_u32_e32 v198, 0x8400, v196
	v_readfirstlane_b32 s55, v197
	global_load_lds_dwordx4 v[44:45], off
	s_addc_u32 s1, s41, 0
	s_mov_b32 m0, s54
	v_readfirstlane_b32 s56, v198
	global_load_lds_dwordx4 v[46:47], off
	v_lshl_add_u64 v[44:45], s[0:1], 0, v[190:191]
	s_mov_b32 m0, s55
	v_lshl_add_u64 v[46:47], s[0:1], 0, v[192:193]
	global_load_lds_dwordx4 v[44:45], off
	s_mov_b32 m0, s56
	s_add_u32 s42, s46, s38
	global_load_lds_dwordx4 v[46:47], off
	s_addc_u32 s43, s47, s39
	s_add_u32 s0, s40, 0xc000
	s_addc_u32 s1, s41, 0
	v_readfirstlane_b32 s54, v200
	s_waitcnt vmcnt(0)
	v_lshlrev_b32_e32 v46, 16, v2
	v_and_b32_e32 v47, 0xffff0000, v2
	v_lshlrev_b32_e32 v44, 16, v3
	v_and_b32_e32 v45, 0xffff0000, v3
	v_lshlrev_b32_e32 v68, 16, v4
	v_and_b32_e32 v69, 0xffff0000, v4
	v_lshlrev_b32_e32 v176, 16, v5
	v_and_b32_e32 v177, 0xffff0000, v5
	v_lshlrev_b32_e32 v76, 16, v6
	v_and_b32_e32 v77, 0xffff0000, v6
	v_lshlrev_b32_e32 v70, 16, v7
	v_and_b32_e32 v71, 0xffff0000, v7
	v_lshlrev_b32_e32 v74, 16, v8
	v_and_b32_e32 v75, 0xffff0000, v8
	v_lshlrev_b32_e32 v72, 16, v9
	v_and_b32_e32 v73, 0xffff0000, v9
	global_load_dwordx4 v[2:5], v[42:43], off offset:208
	global_load_dwordx4 v[6:9], v[42:43], off offset:192
	v_lshlrev_b32_e32 v54, 16, v10
	v_and_b32_e32 v55, 0xffff0000, v10
	v_lshlrev_b32_e32 v52, 16, v11
	v_and_b32_e32 v53, 0xffff0000, v11
	v_lshlrev_b32_e32 v58, 16, v12
	v_and_b32_e32 v59, 0xffff0000, v12
	v_lshlrev_b32_e32 v56, 16, v13
	v_and_b32_e32 v57, 0xffff0000, v13
	v_lshlrev_b32_e32 v174, 16, v14
	v_and_b32_e32 v175, 0xffff0000, v14
	v_lshlrev_b32_e32 v78, 16, v15
	v_and_b32_e32 v79, 0xffff0000, v15
	v_lshlrev_b32_e32 v172, 16, v16
	v_and_b32_e32 v173, 0xffff0000, v16
	v_lshlrev_b32_e32 v80, 16, v17
	v_and_b32_e32 v81, 0xffff0000, v17
	global_load_dwordx4 v[10:13], v[42:43], off offset:240
	global_load_dwordx4 v[14:17], v[42:43], off offset:224
	v_pk_mul_f32 v[216:217], v[76:77], v[76:77]
	v_pk_mul_f32 v[212:213], v[72:73], v[72:73]
	v_add_f32_e32 v166, v216, v217
	v_pk_mul_f32 v[216:217], v[70:71], v[70:71]
	v_lshlrev_b32_e32 v98, 16, v60
	v_add_f32_e32 v166, v166, v216
	v_add_f32_e32 v166, v217, v166
	v_pk_mul_f32 v[216:217], v[74:75], v[74:75]
	v_and_b32_e32 v99, 0xffff0000, v60
	v_add_f32_e32 v166, v216, v166
	v_add_f32_e32 v166, v217, v166
	v_add_f32_e32 v166, v212, v166
	v_add_f32_e32 v166, v213, v166
	v_pk_mul_f32 v[212:213], v[46:47], v[46:47]
	v_pk_mul_f32 v[216:217], v[44:45], v[44:45]
	v_add_f32_e32 v212, v212, v213
	v_add_f32_e32 v212, v212, v216
	v_add_f32_e32 v216, v217, v212
	v_pk_mul_f32 v[212:213], v[68:69], v[68:69]
	v_lshlrev_b32_e32 v152, 16, v61
	v_add_f32_e32 v212, v212, v216
	v_add_f32_e32 v216, v213, v212
	v_pk_mul_f32 v[212:213], v[176:177], v[176:177]
	v_and_b32_e32 v153, 0xffff0000, v61
	v_add_f32_e32 v212, v212, v216
	v_add_f32_e32 v216, v213, v212
	v_pk_mul_f32 v[212:213], v[54:55], v[54:55]
	v_lshlrev_b32_e32 v100, 16, v62
	v_add_f32_e32 v217, v212, v213
	v_pk_mul_f32 v[212:213], v[52:53], v[52:53]
	v_and_b32_e32 v101, 0xffff0000, v62
	v_add_f32_e32 v212, v217, v212
	v_lshlrev_b32_e32 v150, 16, v63
	v_and_b32_e32 v151, 0xffff0000, v63
	v_add_f32_e32 v217, v213, v212
	v_pk_mul_f32 v[212:213], v[58:59], v[58:59]
	v_lshlrev_b32_e32 v90, 16, v30
	v_add_f32_e32 v212, v212, v217
	v_add_f32_e32 v217, v213, v212
	v_pk_mul_f32 v[212:213], v[56:57], v[56:57]
	v_and_b32_e32 v91, 0xffff0000, v30
	v_lshlrev_b32_e32 v160, 16, v31
	v_and_b32_e32 v161, 0xffff0000, v31
	v_lshlrev_b32_e32 v102, 16, v48
	v_and_b32_e32 v103, 0xffff0000, v48
	v_lshlrev_b32_e32 v148, 16, v49
	v_and_b32_e32 v149, 0xffff0000, v49
	v_lshlrev_b32_e32 v104, 16, v50
	v_and_b32_e32 v105, 0xffff0000, v50
	v_lshlrev_b32_e32 v146, 16, v51
	v_and_b32_e32 v147, 0xffff0000, v51
	v_add_f32_e32 v212, v212, v217
	v_add_f32_e32 v217, v213, v212
	v_pk_mul_f32 v[212:213], v[174:175], v[174:175]
	v_lshlrev_b32_e32 v82, 16, v18
	v_add_f32_e32 v218, v212, v213
	v_pk_mul_f32 v[212:213], v[78:79], v[78:79]
	v_and_b32_e32 v83, 0xffff0000, v18
	v_add_f32_e32 v212, v218, v212
	v_lshlrev_b32_e32 v170, 16, v19
	v_and_b32_e32 v171, 0xffff0000, v19
	s_waitcnt vmcnt(0)
	v_lshlrev_b32_e32 v64, 16, v2
	v_and_b32_e32 v65, 0xffff0000, v2
	v_mbcnt_hi_u32_b32 v2, -1, v227
	v_lshlrev_b32_e32 v60, 16, v4
	v_and_b32_e32 v61, 0xffff0000, v4
	v_and_b32_e32 v4, 64, v2
	v_lshlrev_b32_e32 v62, 16, v3
	v_and_b32_e32 v63, 0xffff0000, v3
	v_xor_b32_e32 v3, 32, v2
	v_add_u32_e32 v4, 64, v4
	v_cmp_lt_i32_e32 vcc, v3, v4
	v_lshlrev_b32_e32 v114, 16, v6
	v_and_b32_e32 v115, 0xffff0000, v6
	v_cndmask_b32_e32 v2, v2, v3, vcc
	v_lshlrev_b32_e32 v120, 16, v7
	v_and_b32_e32 v121, 0xffff0000, v7
	v_lshlrev_b32_e32 v116, 16, v8
	v_and_b32_e32 v117, 0xffff0000, v8
	v_lshlrev_b32_e32 v118, 16, v9
	v_and_b32_e32 v119, 0xffff0000, v9
	v_lshlrev_b32_e32 v30, 16, v5
	v_and_b32_e32 v31, 0xffff0000, v5
	v_lshlrev_b32_e32 v189, 2, v2
	global_load_dwordx4 v[2:5], v[180:181], off offset:496
	global_load_dwordx4 v[6:9], v[180:181], off offset:480
	global_load_dwordx4 v[202:205], v[180:181], off offset:16
	global_load_dwordx4 v[48:51], v[180:181], off
	v_pk_mul_f32 v[208:209], v[82:83], v[82:83]
	v_add_f32_e32 v218, v213, v212
	v_pk_mul_f32 v[212:213], v[172:173], v[172:173]
	v_pk_mul_f32 v[206:207], v[170:171], v[170:171]
	v_add_f32_e32 v212, v212, v218
	v_add_f32_e32 v208, v208, v209
	v_lshlrev_b32_e32 v168, 16, v20
	v_and_b32_e32 v169, 0xffff0000, v20
	v_pk_mul_f32 v[210:211], v[80:81], v[80:81]
	v_add_f32_e32 v212, v213, v212
	v_add_f32_e32 v206, v208, v206
	v_pk_mul_f32 v[214:215], v[168:169], v[168:169]
	v_add_f32_e32 v210, v210, v212
	v_add_f32_e32 v166, v216, v166
	v_add_f32_e32 v216, v207, v206
	v_add_f32_e32 v218, v211, v210
	v_add_f32_e32 v166, v166, v217
	v_add_f32_e32 v214, v214, v216
	global_load_dwordx4 v[206:209], v[180:181], off offset:80
	global_load_dwordx4 v[210:213], v[180:181], off offset:64
	v_add_f32_e32 v166, v166, v218
	v_add_f32_e32 v218, v215, v214
	global_load_dwordx4 v[214:217], v[180:181], off offset:32
	global_load_dwordx4 v[234:237], v[180:181], off offset:48
	v_and_b32_e32 v127, 0xffff0000, v14
	v_and_b32_e32 v131, 0xffff0000, v10
	v_lshlrev_b32_e32 v88, 16, v24
	v_and_b32_e32 v89, 0xffff0000, v24
	v_lshlrev_b32_e32 v162, 16, v25
	v_and_b32_e32 v163, 0xffff0000, v25
	v_lshlrev_b32_e32 v126, 16, v14
	v_lshlrev_b32_e32 v130, 16, v10
	v_mov_b32_e32 v24, v127
	v_mov_b32_e32 v25, v131
	v_lshlrev_b32_e32 v164, 16, v22
	v_and_b32_e32 v165, 0xffff0000, v22
	v_lshlrev_b32_e32 v86, 16, v23
	v_and_b32_e32 v87, 0xffff0000, v23
	v_lshlrev_b32_e32 v136, 16, v15
	v_lshlrev_b32_e32 v132, 16, v11
	v_mov_b32_e32 v22, v126
	v_mov_b32_e32 v23, v130
	v_pk_mul_f32 v[24:25], v[24:25], v[24:25]
	v_lshlrev_b32_e32 v94, 16, v26
	v_and_b32_e32 v95, 0xffff0000, v26
	v_lshlrev_b32_e32 v156, 16, v27
	v_and_b32_e32 v157, 0xffff0000, v27
	v_and_b32_e32 v137, 0xffff0000, v15
	v_and_b32_e32 v133, 0xffff0000, v11
	v_mov_b32_e32 v18, v136
	v_mov_b32_e32 v19, v132
	v_pk_fma_f32 v[22:23], v[22:23], v[22:23], v[24:25]
	v_mov_b32_e32 v26, v115
	v_mov_b32_e32 v27, v65
	v_lshlrev_b32_e32 v84, 16, v21
	v_and_b32_e32 v85, 0xffff0000, v21
	v_and_b32_e32 v107, 0xffff0000, v38
	v_and_b32_e32 v111, 0xffff0000, v34
	v_lshlrev_b32_e32 v128, 16, v16
	v_lshlrev_b32_e32 v124, 16, v12
	v_mov_b32_e32 v20, v137
	v_mov_b32_e32 v21, v133
	v_pk_fma_f32 v[18:19], v[18:19], v[18:19], v[22:23]
	v_mov_b32_e32 v24, v114
	v_mov_b32_e32 v25, v64
	v_pk_mul_f32 v[26:27], v[26:27], v[26:27]
	v_lshlrev_b32_e32 v96, 16, v28
	v_and_b32_e32 v97, 0xffff0000, v28
	v_lshlrev_b32_e32 v154, 16, v29
	v_and_b32_e32 v155, 0xffff0000, v29
	v_lshlrev_b32_e32 v106, 16, v38
	v_lshlrev_b32_e32 v110, 16, v34
	v_and_b32_e32 v129, 0xffff0000, v16
	v_and_b32_e32 v125, 0xffff0000, v12
	v_mov_b32_e32 v14, v128
	v_mov_b32_e32 v15, v124
	v_pk_fma_f32 v[18:19], v[20:21], v[20:21], v[18:19]
	v_mov_b32_e32 v20, v120
	v_mov_b32_e32 v21, v62
	v_pk_fma_f32 v[24:25], v[24:25], v[24:25], v[26:27]
	v_mov_b32_e32 v28, v107
	v_mov_b32_e32 v29, v111
	v_lshlrev_b32_e32 v144, 16, v39
	v_lshlrev_b32_e32 v140, 16, v35
	v_lshlrev_b32_e32 v134, 16, v17
	v_and_b32_e32 v135, 0xffff0000, v17
	v_mov_b32_e32 v16, v129
	v_mov_b32_e32 v17, v125
	v_pk_fma_f32 v[14:15], v[14:15], v[14:15], v[18:19]
	v_mov_b32_e32 v22, v121
	v_mov_b32_e32 v23, v63
	v_pk_fma_f32 v[20:21], v[20:21], v[20:21], v[24:25]
	v_mov_b32_e32 v26, v106
	v_mov_b32_e32 v27, v110
	v_pk_mul_f32 v[28:29], v[28:29], v[28:29]
	v_lshlrev_b32_e32 v92, 16, v32
	v_and_b32_e32 v93, 0xffff0000, v32
	v_lshlrev_b32_e32 v158, 16, v33
	v_and_b32_e32 v159, 0xffff0000, v33
	v_and_b32_e32 v145, 0xffff0000, v39
	v_and_b32_e32 v141, 0xffff0000, v35
	v_lshlrev_b32_e32 v122, 16, v13
	v_pk_fma_f32 v[14:15], v[16:17], v[16:17], v[14:15]
	v_mov_b32_e32 v16, v116
	v_mov_b32_e32 v17, v60
	v_pk_fma_f32 v[20:21], v[22:23], v[22:23], v[20:21]
	v_mov_b32_e32 v22, v144
	v_mov_b32_e32 v23, v140
	v_pk_fma_f32 v[26:27], v[26:27], v[26:27], v[28:29]
	v_mov_b32_e32 v32, v99
	v_mov_b32_e32 v33, v103
	v_lshlrev_b32_e32 v108, 16, v40
	v_lshlrev_b32_e32 v112, 16, v36
	v_and_b32_e32 v123, 0xffff0000, v13
	v_mov_b32_e32 v10, v134
	v_mov_b32_e32 v11, v122
	v_mov_b32_e32 v18, v117
	v_mov_b32_e32 v19, v61
	v_pk_fma_f32 v[16:17], v[16:17], v[16:17], v[20:21]
	v_mov_b32_e32 v24, v145
	v_mov_b32_e32 v25, v141
	v_pk_fma_f32 v[22:23], v[22:23], v[22:23], v[26:27]
	v_mov_b32_e32 v28, v98
	v_mov_b32_e32 v29, v102
	v_pk_mul_f32 v[32:33], v[32:33], v[32:33]
	v_and_b32_e32 v109, 0xffff0000, v40
	v_and_b32_e32 v113, 0xffff0000, v36
	v_mov_b32_e32 v12, v135
	v_mov_b32_e32 v13, v123
	v_pk_fma_f32 v[10:11], v[10:11], v[10:11], v[14:15]
	v_pk_fma_f32 v[16:17], v[18:19], v[18:19], v[16:17]
	v_mov_b32_e32 v18, v108
	v_mov_b32_e32 v19, v112
	v_pk_fma_f32 v[22:23], v[24:25], v[24:25], v[22:23]
	v_mov_b32_e32 v24, v152
	v_mov_b32_e32 v25, v148
	v_pk_fma_f32 v[28:29], v[28:29], v[28:29], v[32:33]
	v_pk_fma_f32 v[10:11], v[12:13], v[12:13], v[10:11]
	v_mov_b32_e32 v12, v118
	v_mov_b32_e32 v13, v30
	v_mov_b32_e32 v20, v109
	v_mov_b32_e32 v21, v113
	v_pk_fma_f32 v[18:19], v[18:19], v[18:19], v[22:23]
	v_mov_b32_e32 v26, v153
	v_mov_b32_e32 v27, v149
	v_pk_fma_f32 v[24:25], v[24:25], v[24:25], v[28:29]
	v_pk_mul_f32 v[42:43], v[164:165], v[164:165]
	v_lshlrev_b32_e32 v142, 16, v41
	v_and_b32_e32 v143, 0xffff0000, v41
	v_lshlrev_b32_e32 v138, 16, v37
	v_mov_b32_e32 v14, v119
	v_mov_b32_e32 v15, v31
	v_pk_fma_f32 v[12:13], v[12:13], v[12:13], v[16:17]
	v_pk_fma_f32 v[18:19], v[20:21], v[20:21], v[18:19]
	v_mov_b32_e32 v20, v100
	v_mov_b32_e32 v21, v104
	v_pk_fma_f32 v[24:25], v[26:27], v[26:27], v[24:25]
	v_pk_mul_f32 v[34:35], v[90:91], v[90:91]
	v_pk_mul_f32 v[40:41], v[86:87], v[86:87]
	v_add_f32_e32 v42, v42, v43
	v_and_b32_e32 v139, 0xffff0000, v37
	v_pk_fma_f32 v[12:13], v[14:15], v[14:15], v[12:13]
	v_mov_b32_e32 v14, v142
	v_mov_b32_e32 v15, v138
	v_mov_b32_e32 v22, v101
	v_mov_b32_e32 v23, v105
	v_pk_fma_f32 v[20:21], v[20:21], v[20:21], v[24:25]
	v_pk_mul_f32 v[24:25], v[94:95], v[94:95]
	v_pk_mul_f32 v[32:33], v[160:161], v[160:161]
	v_add_f32_e32 v40, v42, v40
	v_add_f32_e32 v34, v34, v35
	v_mov_b32_e32 v16, v143
	v_mov_b32_e32 v17, v139
	v_pk_fma_f32 v[14:15], v[14:15], v[14:15], v[18:19]
	v_pk_fma_f32 v[20:21], v[22:23], v[22:23], v[20:21]
	v_pk_mul_f32 v[22:23], v[156:157], v[156:157]
	v_pk_mul_f32 v[38:39], v[88:89], v[88:89]
	v_add_f32_e32 v40, v41, v40
	v_add_f32_e32 v32, v34, v32
	v_add_f32_e32 v24, v24, v25
	v_pk_fma_f32 v[14:15], v[16:17], v[16:17], v[14:15]
	v_mov_b32_e32 v16, v150
	v_mov_b32_e32 v17, v146
	v_pk_mul_f32 v[28:29], v[92:93], v[92:93]
	v_pk_mul_f32 v[66:67], v[84:85], v[84:85]
	v_add_f32_e32 v38, v38, v40
	v_add_f32_e32 v32, v33, v32
	v_add_f32_e32 v22, v24, v22
	v_pk_fma_f32 v[16:17], v[16:17], v[16:17], v[20:21]
	v_pk_mul_f32 v[20:21], v[96:97], v[96:97]
	v_pk_mul_f32 v[36:37], v[162:163], v[162:163]
	v_add_f32_e32 v66, v66, v218
	v_add_f32_e32 v38, v39, v38
	v_add_f32_e32 v28, v28, v32
	v_add_f32_e32 v22, v23, v22
	v_mov_b32_e32 v18, v151
	v_mov_b32_e32 v19, v147
	v_pk_mul_f32 v[26:27], v[158:159], v[158:159]
	v_add_f32_e32 v66, v67, v66
	v_add_f32_e32 v36, v36, v38
	v_add_f32_e32 v28, v29, v28
	v_add_f32_e32 v20, v20, v22
	v_pk_fma_f32 v[16:17], v[18:19], v[18:19], v[16:17]
	v_pk_mul_f32 v[18:19], v[154:155], v[154:155]
	v_add_f32_e32 v66, v166, v66
	v_add_f32_e32 v36, v37, v36
	v_add_f32_e32 v26, v26, v28
	v_add_f32_e32 v20, v21, v20
	v_add_f32_e32 v36, v66, v36
	v_add_f32_e32 v26, v27, v26
	v_add_f32_e32 v18, v18, v20
	v_add_f32_e32 v26, v36, v26
	v_add_f32_e32 v18, v19, v18
	v_add_f32_e32 v18, v26, v18
	v_add_f32_e32 v16, v18, v16
	v_add_f32_e32 v16, v16, v17
	v_add_f32_e32 v14, v16, v14
	v_add_f32_e32 v14, v14, v15
	v_add_f32_e32 v12, v14, v12
	v_add_f32_e32 v12, v12, v13
	v_add_f32_e32 v10, v12, v10
	v_add_f32_e32 v22, v10, v11
	ds_bpermute_b32 v23, v189, v22
	global_load_dwordx4 v[10:13], v[180:181], off offset:464
	global_load_dwordx4 v[14:17], v[180:181], off offset:448
	global_load_dwordx4 v[32:35], v[180:181], off offset:432
	global_load_dwordx4 v[18:21], v[180:181], off offset:416
	s_waitcnt lgkmcnt(0)
	v_add_f32_e32 v22, v22, v23
	v_fmamk_f32 v22, v22, 0x3b800000, v221
	v_rsq_f32_e32 v166, v22
	global_load_dwordx4 v[22:25], v[180:181], off offset:400
	global_load_dwordx4 v[26:29], v[180:181], off offset:384
	global_load_dwordx4 v[36:39], v[180:181], off offset:368
	global_load_dwordx4 v[40:43], v[180:181], off offset:352
	v_pk_mul_f32 v[46:47], v[166:167], v[46:47] op_sel_hi:[0,1]
	v_pk_mul_f32 v[44:45], v[166:167], v[44:45] op_sel_hi:[0,1]
	v_pk_mul_f32 v[68:69], v[166:167], v[68:69] op_sel_hi:[0,1]
	v_pk_mul_f32 v[176:177], v[166:167], v[176:177] op_sel_hi:[0,1]
	s_waitcnt vmcnt(12)
	v_pk_mul_f32 v[66:67], v[48:49], v[46:47]
	v_pk_mul_f32 v[218:219], v[50:51], v[44:45]
	global_load_dwordx4 v[44:47], v[180:181], off offset:336
	global_load_dwordx4 v[48:51], v[180:181], off offset:320
	v_pk_mul_f32 v[68:69], v[202:203], v[68:69]
	v_pk_mul_f32 v[176:177], v[204:205], v[176:177]
	global_load_dwordx4 v[202:205], v[180:181], off offset:112
	global_load_dwordx4 v[238:241], v[180:181], off offset:96
	v_cvt_pk_bf16_f32 v66, v66, v67
	v_cvt_pk_bf16_f32 v68, v68, v69
	v_cvt_pk_bf16_f32 v69, v176, v177
	v_and_b32_e32 v177, 0xffff0000, v66
	v_cvt_pk_bf16_f32 v67, v218, v219
	v_lshlrev_b32_e32 v176, 16, v66
	v_mul_f32_e32 v218, v177, v177
	v_fmac_f32_e32 v218, v176, v176
	v_lshlrev_b32_e32 v176, 16, v67
	v_fmac_f32_e32 v218, v176, v176
	v_and_b32_e32 v176, 0xffff0000, v67
	v_fmac_f32_e32 v218, v176, v176
	v_lshlrev_b32_e32 v176, 16, v68
	v_fmac_f32_e32 v218, v176, v176
	v_and_b32_e32 v176, 0xffff0000, v68
	v_fmac_f32_e32 v218, v176, v176
	v_lshlrev_b32_e32 v176, 16, v69
	v_pk_mul_f32 v[76:77], v[166:167], v[76:77] op_sel_hi:[0,1]
	v_fmac_f32_e32 v218, v176, v176
	v_and_b32_e32 v176, 0xffff0000, v69
	s_waitcnt vmcnt(13)
	v_pk_mul_f32 v[76:77], v[214:215], v[76:77]
	v_pk_mul_f32 v[70:71], v[166:167], v[70:71] op_sel_hi:[0,1]
	v_pk_mul_f32 v[74:75], v[166:167], v[74:75] op_sel_hi:[0,1]
	v_pk_mul_f32 v[72:73], v[166:167], v[72:73] op_sel_hi:[0,1]
	v_fmac_f32_e32 v218, v176, v176
	v_pk_mul_f32 v[176:177], v[70:71], v[216:217]
	v_cvt_pk_bf16_f32 v70, v76, v77
	s_waitcnt vmcnt(12)
	v_pk_mul_f32 v[74:75], v[74:75], v[234:235]
	v_pk_mul_f32 v[76:77], v[72:73], v[236:237]
	global_load_dwordx4 v[214:217], v[180:181], off offset:144
	global_load_dwordx4 v[234:237], v[180:181], off offset:128
	v_cvt_pk_bf16_f32 v72, v74, v75
	v_and_b32_e32 v75, 0xffff0000, v70
	v_cvt_pk_bf16_f32 v71, v176, v177
	v_lshlrev_b32_e32 v74, 16, v70
	v_mul_f32_e32 v75, v75, v75
	v_fmac_f32_e32 v75, v74, v74
	v_lshlrev_b32_e32 v74, 16, v71
	v_fmac_f32_e32 v75, v74, v74
	v_and_b32_e32 v74, 0xffff0000, v71
	v_fmac_f32_e32 v75, v74, v74
	v_lshlrev_b32_e32 v74, 16, v72
	v_cvt_pk_bf16_f32 v73, v76, v77
	v_fmac_f32_e32 v75, v74, v74
	v_and_b32_e32 v74, 0xffff0000, v72
	v_fmac_f32_e32 v75, v74, v74
	v_lshlrev_b32_e32 v74, 16, v73
	v_fmac_f32_e32 v75, v74, v74
	v_and_b32_e32 v74, 0xffff0000, v73
	v_pk_mul_f32 v[52:53], v[166:167], v[52:53] op_sel_hi:[0,1]
	v_fmac_f32_e32 v75, v74, v74
	v_pk_mul_f32 v[54:55], v[166:167], v[54:55] op_sel_hi:[0,1]
	v_pk_mul_f32 v[52:53], v[52:53], v[212:213]
	v_add_f32_e32 v176, v218, v75
	v_pk_mul_f32 v[54:55], v[54:55], v[210:211]
	v_cvt_pk_bf16_f32 v75, v52, v53
	v_pk_mul_f32 v[52:53], v[166:167], v[58:59] op_sel_hi:[0,1]
	v_cvt_pk_bf16_f32 v74, v54, v55
	v_pk_mul_f32 v[52:53], v[52:53], v[206:207]
	v_pk_mul_f32 v[54:55], v[166:167], v[56:57] op_sel_hi:[0,1]
	v_cvt_pk_bf16_f32 v76, v52, v53
	v_and_b32_e32 v53, 0xffff0000, v74
	v_lshlrev_b32_e32 v52, 16, v74
	v_mul_f32_e32 v177, v53, v53
	v_fmac_f32_e32 v177, v52, v52
	v_lshlrev_b32_e32 v52, 16, v75
	v_fmac_f32_e32 v177, v52, v52
	v_and_b32_e32 v52, 0xffff0000, v75
	v_pk_mul_f32 v[54:55], v[54:55], v[208:209]
	v_fmac_f32_e32 v177, v52, v52
	v_lshlrev_b32_e32 v52, 16, v76
	v_cvt_pk_bf16_f32 v77, v54, v55
	v_fmac_f32_e32 v177, v52, v52
	v_and_b32_e32 v52, 0xffff0000, v76
	v_fmac_f32_e32 v177, v52, v52
	v_lshlrev_b32_e32 v52, 16, v77
	v_fmac_f32_e32 v177, v52, v52
	v_and_b32_e32 v52, 0xffff0000, v77
	v_fmac_f32_e32 v177, v52, v52
	v_pk_mul_f32 v[174:175], v[166:167], v[174:175] op_sel_hi:[0,1]
	v_pk_mul_f32 v[78:79], v[166:167], v[78:79] op_sel_hi:[0,1]
	v_add_f32_e32 v233, v176, v177
	s_waitcnt vmcnt(2)
	v_pk_mul_f32 v[174:175], v[174:175], v[238:239]
	v_pk_mul_f32 v[176:177], v[78:79], v[240:241]
	v_pk_mul_f32 v[172:173], v[166:167], v[172:173] op_sel_hi:[0,1]
	v_cvt_pk_bf16_f32 v78, v174, v175
	v_cvt_pk_bf16_f32 v79, v176, v177
	v_pk_mul_f32 v[176:177], v[172:173], v[202:203]
	v_pk_mul_f32 v[80:81], v[166:167], v[80:81] op_sel_hi:[0,1]
	v_pk_mul_f32 v[218:219], v[80:81], v[204:205]
	v_cvt_pk_bf16_f32 v80, v176, v177
	v_and_b32_e32 v177, 0xffff0000, v78
	v_lshlrev_b32_e32 v176, 16, v78
	v_mul_f32_e32 v177, v177, v177
	v_fmac_f32_e32 v177, v176, v176
	v_lshlrev_b32_e32 v176, 16, v79
	v_fmac_f32_e32 v177, v176, v176
	v_and_b32_e32 v176, 0xffff0000, v79
	v_fmac_f32_e32 v177, v176, v176
	v_lshlrev_b32_e32 v176, 16, v80
	v_cvt_pk_bf16_f32 v81, v218, v219
	v_fmac_f32_e32 v177, v176, v176
	v_and_b32_e32 v176, 0xffff0000, v80
	global_load_dwordx4 v[206:209], v[180:181], off offset:176
	global_load_dwordx4 v[210:213], v[180:181], off offset:160
	global_load_dwordx4 v[52:55], v[180:181], off offset:304
	global_load_dwordx4 v[56:59], v[180:181], off offset:288
	v_fmac_f32_e32 v177, v176, v176
	v_lshlrev_b32_e32 v176, 16, v81
	v_fmac_f32_e32 v177, v176, v176
	v_and_b32_e32 v176, 0xffff0000, v81
	v_pk_mul_f32 v[82:83], v[166:167], v[82:83] op_sel_hi:[0,1]
	v_pk_mul_f32 v[170:171], v[166:167], v[170:171] op_sel_hi:[0,1]
	global_load_dwordx4 v[172:175], v[180:181], off offset:208
	global_load_dwordx4 v[202:205], v[180:181], off offset:192
	v_fmac_f32_e32 v177, v176, v176
	s_waitcnt vmcnt(6)
	v_pk_mul_f32 v[82:83], v[82:83], v[234:235]
	v_pk_mul_f32 v[170:171], v[170:171], v[236:237]
	v_pk_mul_f32 v[168:169], v[166:167], v[168:169] op_sel_hi:[0,1]
	v_pk_mul_f32 v[84:85], v[166:167], v[84:85] op_sel_hi:[0,1]
	v_add_f32_e32 v233, v233, v177
	v_cvt_pk_bf16_f32 v82, v82, v83
	v_cvt_pk_bf16_f32 v83, v170, v171
	v_pk_mul_f32 v[176:177], v[168:169], v[214:215]
	v_pk_mul_f32 v[218:219], v[84:85], v[216:217]
	global_load_dwordx4 v[168:171], v[180:181], off offset:240
	global_load_dwordx4 v[214:217], v[180:181], off offset:224
	global_load_dwordx4 v[234:237], v[180:181], off offset:272
	global_load_dwordx4 v[238:241], v[180:181], off offset:256
	v_cvt_pk_bf16_f32 v84, v176, v177
	v_and_b32_e32 v177, 0xffff0000, v82
	v_lshlrev_b32_e32 v176, 16, v82
	v_mul_f32_e32 v177, v177, v177
	v_fmac_f32_e32 v177, v176, v176
	v_lshlrev_b32_e32 v176, 16, v83
	v_fmac_f32_e32 v177, v176, v176
	v_and_b32_e32 v176, 0xffff0000, v83
	v_fmac_f32_e32 v177, v176, v176
	v_lshlrev_b32_e32 v176, 16, v84
	v_cvt_pk_bf16_f32 v85, v218, v219
	v_fmac_f32_e32 v177, v176, v176
	v_and_b32_e32 v176, 0xffff0000, v84
	v_fmac_f32_e32 v177, v176, v176
	v_lshlrev_b32_e32 v176, 16, v85
	v_pk_mul_f32 v[102:103], v[166:167], v[102:103] op_sel_hi:[0,1]
	v_fmac_f32_e32 v177, v176, v176
	v_and_b32_e32 v176, 0xffff0000, v85
	v_pk_mul_f32 v[164:165], v[166:167], v[164:165] op_sel_hi:[0,1]
	v_fmac_f32_e32 v177, v176, v176
	v_pk_mul_f32 v[86:87], v[166:167], v[86:87] op_sel_hi:[0,1]
	v_pk_mul_f32 v[88:89], v[166:167], v[88:89] op_sel_hi:[0,1]
	v_pk_mul_f32 v[162:163], v[166:167], v[162:163] op_sel_hi:[0,1]
	v_pk_mul_f32 v[90:91], v[166:167], v[90:91] op_sel_hi:[0,1]
	v_add_f32_e32 v218, v233, v177
	v_pk_mul_f32 v[92:93], v[166:167], v[92:93] op_sel_hi:[0,1]
	v_pk_mul_f32 v[158:159], v[166:167], v[158:159] op_sel_hi:[0,1]
	v_pk_mul_f32 v[94:95], v[166:167], v[94:95] op_sel_hi:[0,1]
	v_pk_mul_f32 v[160:161], v[166:167], v[160:161] op_sel_hi:[0,1]
	v_pk_mul_f32 v[96:97], v[166:167], v[96:97] op_sel_hi:[0,1]
	v_pk_mul_f32 v[154:155], v[166:167], v[154:155] op_sel_hi:[0,1]
	v_pk_mul_f32 v[98:99], v[166:167], v[98:99] op_sel_hi:[0,1]
	v_pk_mul_f32 v[156:157], v[166:167], v[156:157] op_sel_hi:[0,1]
	v_pk_mul_f32 v[100:101], v[166:167], v[100:101] op_sel_hi:[0,1]
	v_pk_mul_f32 v[150:151], v[166:167], v[150:151] op_sel_hi:[0,1]
	v_pk_mul_f32 v[152:153], v[166:167], v[152:153] op_sel_hi:[0,1]
	s_waitcnt vmcnt(4)
	s_barrier
	s_waitcnt vmcnt(9)
	v_pk_mul_f32 v[88:89], v[88:89], v[206:207]
	s_waitcnt vmcnt(8)
	v_pk_mul_f32 v[164:165], v[164:165], v[210:211]
	s_waitcnt vmcnt(6)
	v_pk_mul_f32 v[56:57], v[102:103], v[56:57]
	v_pk_mul_f32 v[176:177], v[86:87], v[212:213]
	v_cvt_pk_bf16_f32 v102, v56, v57
	v_pk_mul_f32 v[56:57], v[166:167], v[148:149] op_sel_hi:[0,1]
	v_cvt_pk_bf16_f32 v86, v164, v165
	v_pk_mul_f32 v[162:163], v[162:163], v[208:209]
	v_pk_mul_f32 v[56:57], v[56:57], v[58:59]
	s_waitcnt vmcnt(4)
	v_pk_mul_f32 v[90:91], v[90:91], v[202:203]
	v_cvt_pk_bf16_f32 v88, v88, v89
	v_cvt_pk_bf16_f32 v89, v162, v163
	v_and_b32_e32 v163, 0xffff0000, v86
	v_cvt_pk_bf16_f32 v90, v90, v91
	v_pk_mul_f32 v[92:93], v[92:93], v[172:173]
	v_pk_mul_f32 v[158:159], v[158:159], v[174:175]
	v_cvt_pk_bf16_f32 v103, v56, v57
	v_pk_mul_f32 v[56:57], v[166:167], v[104:105] op_sel_hi:[0,1]
	v_cvt_pk_bf16_f32 v87, v176, v177
	v_lshlrev_b32_e32 v162, 16, v86
	s_waitcnt vmcnt(2)
	v_pk_mul_f32 v[94:95], v[94:95], v[214:215]
	v_mul_f32_e32 v163, v163, v163
	v_pk_mul_f32 v[160:161], v[160:161], v[204:205]
	v_cvt_pk_bf16_f32 v92, v92, v93
	v_cvt_pk_bf16_f32 v93, v158, v159
	v_and_b32_e32 v159, 0xffff0000, v90
	v_cvt_pk_bf16_f32 v94, v94, v95
	v_pk_mul_f32 v[96:97], v[96:97], v[168:169]
	v_pk_mul_f32 v[154:155], v[154:155], v[170:171]
	s_waitcnt vmcnt(0)
	v_pk_mul_f32 v[98:99], v[98:99], v[238:239]
	v_pk_mul_f32 v[52:53], v[56:57], v[52:53]
	v_fmac_f32_e32 v163, v162, v162
	v_lshlrev_b32_e32 v162, 16, v87
	v_cvt_pk_bf16_f32 v91, v160, v161
	v_lshlrev_b32_e32 v158, 16, v90
	v_mul_f32_e32 v159, v159, v159
	v_pk_mul_f32 v[156:157], v[156:157], v[216:217]
	v_cvt_pk_bf16_f32 v96, v96, v97
	v_cvt_pk_bf16_f32 v97, v154, v155
	v_and_b32_e32 v155, 0xffff0000, v94
	v_cvt_pk_bf16_f32 v98, v98, v99
	v_pk_mul_f32 v[100:101], v[100:101], v[234:235]
	v_pk_mul_f32 v[150:151], v[150:151], v[236:237]
	v_cvt_pk_bf16_f32 v104, v52, v53
	v_pk_mul_f32 v[52:53], v[166:167], v[146:147] op_sel_hi:[0,1]
	v_fmac_f32_e32 v163, v162, v162
	v_and_b32_e32 v162, 0xffff0000, v87
	v_fmac_f32_e32 v159, v158, v158
	v_lshlrev_b32_e32 v158, 16, v91
	v_cvt_pk_bf16_f32 v95, v156, v157
	v_lshlrev_b32_e32 v154, 16, v94
	v_mul_f32_e32 v155, v155, v155
	v_pk_mul_f32 v[152:153], v[152:153], v[240:241]
	v_cvt_pk_bf16_f32 v100, v100, v101
	v_cvt_pk_bf16_f32 v101, v150, v151
	v_and_b32_e32 v151, 0xffff0000, v98
	v_pk_mul_f32 v[52:53], v[52:53], v[54:55]
	v_fmac_f32_e32 v163, v162, v162
	v_lshlrev_b32_e32 v162, 16, v88
	v_fmac_f32_e32 v159, v158, v158
	v_and_b32_e32 v158, 0xffff0000, v91
	v_fmac_f32_e32 v155, v154, v154
	v_lshlrev_b32_e32 v154, 16, v95
	v_cvt_pk_bf16_f32 v99, v152, v153
	v_lshlrev_b32_e32 v150, 16, v98
	v_mul_f32_e32 v151, v151, v151
	v_cvt_pk_bf16_f32 v105, v52, v53
	v_and_b32_e32 v53, 0xffff0000, v102
	v_fmac_f32_e32 v163, v162, v162
	v_and_b32_e32 v162, 0xffff0000, v88
	v_fmac_f32_e32 v159, v158, v158
	v_lshlrev_b32_e32 v158, 16, v92
	v_fmac_f32_e32 v155, v154, v154
	v_and_b32_e32 v154, 0xffff0000, v95
	v_fmac_f32_e32 v151, v150, v150
	v_lshlrev_b32_e32 v150, 16, v99
	v_lshlrev_b32_e32 v52, 16, v102
	v_mul_f32_e32 v53, v53, v53
	v_fmac_f32_e32 v163, v162, v162
	v_lshlrev_b32_e32 v162, 16, v89
	v_fmac_f32_e32 v159, v158, v158
	v_and_b32_e32 v158, 0xffff0000, v92
	v_fmac_f32_e32 v155, v154, v154
	v_lshlrev_b32_e32 v154, 16, v96
	v_fmac_f32_e32 v151, v150, v150
	v_and_b32_e32 v150, 0xffff0000, v99
	v_fmac_f32_e32 v53, v52, v52
	v_lshlrev_b32_e32 v52, 16, v103
	v_fmac_f32_e32 v163, v162, v162
	v_and_b32_e32 v162, 0xffff0000, v89
	v_fmac_f32_e32 v159, v158, v158
	v_lshlrev_b32_e32 v158, 16, v93
	v_fmac_f32_e32 v155, v154, v154
	v_and_b32_e32 v154, 0xffff0000, v96
	v_fmac_f32_e32 v151, v150, v150
	v_lshlrev_b32_e32 v150, 16, v100
	v_fmac_f32_e32 v53, v52, v52
	v_and_b32_e32 v52, 0xffff0000, v103
	v_fmac_f32_e32 v163, v162, v162
	v_fmac_f32_e32 v159, v158, v158
	v_and_b32_e32 v158, 0xffff0000, v93
	v_fmac_f32_e32 v155, v154, v154
	v_lshlrev_b32_e32 v154, 16, v97
	v_fmac_f32_e32 v151, v150, v150
	v_and_b32_e32 v150, 0xffff0000, v100
	v_fmac_f32_e32 v53, v52, v52
	v_lshlrev_b32_e32 v52, 16, v104
	v_add_f32_e32 v162, v218, v163
	v_fmac_f32_e32 v159, v158, v158
	v_fmac_f32_e32 v155, v154, v154
	v_and_b32_e32 v154, 0xffff0000, v97
	v_fmac_f32_e32 v151, v150, v150
	v_lshlrev_b32_e32 v150, 16, v101
	v_fmac_f32_e32 v53, v52, v52
	v_and_b32_e32 v52, 0xffff0000, v104
	v_add_f32_e32 v158, v162, v159
	v_fmac_f32_e32 v155, v154, v154
	v_fmac_f32_e32 v151, v150, v150
	v_and_b32_e32 v150, 0xffff0000, v101
	v_fmac_f32_e32 v53, v52, v52
	v_lshlrev_b32_e32 v52, 16, v105
	v_add_f32_e32 v154, v158, v155
	v_fmac_f32_e32 v151, v150, v150
	v_fmac_f32_e32 v53, v52, v52
	v_and_b32_e32 v52, 0xffff0000, v105
	v_add_f32_e32 v150, v154, v151
	v_fmac_f32_e32 v53, v52, v52
	v_add_f32_e32 v54, v150, v53
	v_pk_mul_f32 v[52:53], v[166:167], v[106:107] op_sel_hi:[0,1]
	v_pk_mul_f32 v[48:49], v[52:53], v[48:49]
	v_add_u32_e32 v151, 0xc000, v196
	v_cvt_pk_bf16_f32 v106, v48, v49
	v_pk_mul_f32 v[48:49], v[166:167], v[144:145] op_sel_hi:[0,1]
	v_pk_mul_f32 v[48:49], v[48:49], v[50:51]
	v_readfirstlane_b32 s16, v151
	v_cvt_pk_bf16_f32 v107, v48, v49
	v_pk_mul_f32 v[48:49], v[166:167], v[108:109] op_sel_hi:[0,1]
	v_pk_mul_f32 v[44:45], v[48:49], v[44:45]
	s_mov_b32 m0, s16
	v_cvt_pk_bf16_f32 v108, v44, v45
	v_pk_mul_f32 v[44:45], v[166:167], v[142:143] op_sel_hi:[0,1]
	v_pk_mul_f32 v[44:45], v[44:45], v[46:47]
	v_add_u32_e32 v152, 0xc400, v196
	v_cvt_pk_bf16_f32 v109, v44, v45
	v_and_b32_e32 v45, 0xffff0000, v106
	v_lshlrev_b32_e32 v44, 16, v106
	v_mul_f32_e32 v45, v45, v45
	v_fmac_f32_e32 v45, v44, v44
	v_lshlrev_b32_e32 v44, 16, v107
	v_fmac_f32_e32 v45, v44, v44
	v_and_b32_e32 v44, 0xffff0000, v107
	v_fmac_f32_e32 v45, v44, v44
	v_lshlrev_b32_e32 v44, 16, v108
	v_fmac_f32_e32 v45, v44, v44
	v_and_b32_e32 v44, 0xffff0000, v108
	v_fmac_f32_e32 v45, v44, v44
	v_lshlrev_b32_e32 v44, 16, v109
	v_fmac_f32_e32 v45, v44, v44
	v_and_b32_e32 v44, 0xffff0000, v109
	v_fmac_f32_e32 v45, v44, v44
	v_add_f32_e32 v46, v54, v45
	v_pk_mul_f32 v[44:45], v[166:167], v[110:111] op_sel_hi:[0,1]
	v_pk_mul_f32 v[40:41], v[44:45], v[40:41]
	v_readfirstlane_b32 s16, v196
	v_cvt_pk_bf16_f32 v110, v40, v41
	v_pk_mul_f32 v[40:41], v[166:167], v[140:141] op_sel_hi:[0,1]
	v_pk_mul_f32 v[40:41], v[40:41], v[42:43]
	s_nop 0
	v_cvt_pk_bf16_f32 v111, v40, v41
	v_pk_mul_f32 v[40:41], v[166:167], v[112:113] op_sel_hi:[0,1]
	v_pk_mul_f32 v[36:37], v[40:41], v[36:37]
	v_pk_mul_f32 v[40:41], v[166:167], v[30:31] op_sel_hi:[0,1]
	v_cvt_pk_bf16_f32 v112, v36, v37
	v_pk_mul_f32 v[36:37], v[166:167], v[138:139] op_sel_hi:[0,1]
	v_pk_mul_f32 v[36:37], v[36:37], v[38:39]
	v_pk_mul_f32 v[34:35], v[40:41], v[34:35]
	v_cvt_pk_bf16_f32 v113, v36, v37
	v_and_b32_e32 v37, 0xffff0000, v110
	v_lshlrev_b32_e32 v36, 16, v110
	v_mul_f32_e32 v37, v37, v37
	v_fmac_f32_e32 v37, v36, v36
	v_lshlrev_b32_e32 v36, 16, v111
	v_fmac_f32_e32 v37, v36, v36
	v_and_b32_e32 v36, 0xffff0000, v111
	v_fmac_f32_e32 v37, v36, v36
	v_lshlrev_b32_e32 v36, 16, v112
	v_fmac_f32_e32 v37, v36, v36
	v_and_b32_e32 v36, 0xffff0000, v112
	v_fmac_f32_e32 v37, v36, v36
	v_lshlrev_b32_e32 v36, 16, v113
	v_fmac_f32_e32 v37, v36, v36
	v_and_b32_e32 v36, 0xffff0000, v113
	v_fmac_f32_e32 v37, v36, v36
	v_add_f32_e32 v46, v46, v37
	v_pk_mul_f32 v[36:37], v[166:167], v[114:115] op_sel_hi:[0,1]
	v_pk_mul_f32 v[26:27], v[36:37], v[26:27]
	s_nop 0
	v_cvt_pk_bf16_f32 v114, v26, v27
	v_pk_mul_f32 v[26:27], v[166:167], v[120:121] op_sel_hi:[0,1]
	v_pk_mul_f32 v[26:27], v[26:27], v[28:29]
	v_and_b32_e32 v44, 0xffff0000, v114
	v_cvt_pk_bf16_f32 v115, v26, v27
	v_pk_mul_f32 v[26:27], v[166:167], v[116:117] op_sel_hi:[0,1]
	v_pk_mul_f32 v[22:23], v[26:27], v[22:23]
	v_cvt_pk_bf16_f32 v121, v34, v35
	v_cvt_pk_bf16_f32 v116, v22, v23
	v_pk_mul_f32 v[22:23], v[166:167], v[118:119] op_sel_hi:[0,1]
	v_pk_mul_f32 v[22:23], v[22:23], v[24:25]
	v_lshlrev_b32_e32 v34, 16, v114
	v_cvt_pk_bf16_f32 v117, v22, v23
	v_pk_mul_f32 v[22:23], v[166:167], v[64:65] op_sel_hi:[0,1]
	v_pk_mul_f32 v[18:19], v[22:23], v[18:19]
	v_lshl_add_u64 v[22:23], s[0:1], 0, v[192:193]
	v_cvt_pk_bf16_f32 v118, v18, v19
	v_pk_mul_f32 v[18:19], v[166:167], v[62:63] op_sel_hi:[0,1]
	v_pk_mul_f32 v[18:19], v[18:19], v[20:21]
	v_and_b32_e32 v45, 0xffff0000, v118
	v_cvt_pk_bf16_f32 v119, v18, v19
	v_pk_mul_f32 v[18:19], v[166:167], v[60:61] op_sel_hi:[0,1]
	v_pk_mul_f32 v[18:19], v[18:19], v[32:33]
	v_lshlrev_b32_e32 v35, 16, v118
	v_cvt_pk_bf16_f32 v120, v18, v19
	v_lshl_add_u64 v[18:19], s[0:1], 0, v[190:191]
	global_load_lds_dwordx4 v[18:19], off
	ds_read_b128 v[18:21], v1
	v_readfirstlane_b32 s0, v152
	s_mov_b32 m0, s0
	ds_read_b128 v[40:43], v1 offset:2048
	global_load_lds_dwordx4 v[22:23], off
	ds_read_b128 v[36:39], v1 offset:1024
	s_waitcnt lgkmcnt(2)
	v_mfma_f32_32x32x16_bf16 v[18:33], v[18:21], v[66:69], 0
	s_add_u32 s0, s40, 0x10000
	s_addc_u32 s1, s41, 0
	s_mov_b32 m0, s16
	s_mov_b32 s16, 0
	s_waitcnt lgkmcnt(0)
	v_mfma_f32_32x32x16_bf16 v[50:65], v[36:39], v[70:73], 0
	v_mul_f32_e64 v36, v44, v44
	v_mul_f32_e64 v37, v45, v45
	v_and_b32_e32 v45, 0xffff0000, v119
	v_fma_f32 v34, v34, v34, v36
	v_fma_f32 v35, v35, v35, v37
	v_lshlrev_b32_e32 v37, 16, v119
	v_lshlrev_b32_e32 v36, 16, v115
	v_pk_fma_f32 v[38:39], v[36:37], v[36:37], v[34:35]
	ds_read_b128 v[34:37], v1 offset:3072
	v_and_b32_e32 v44, 0xffff0000, v115
	v_mfma_f32_32x32x16_bf16 v[18:33], v[40:43], v[74:77], v[18:33]
	v_fma_f32 v38, v44, v44, v38
	v_fma_f32 v39, v45, v45, v39
	v_lshlrev_b32_e32 v41, 16, v120
	v_lshlrev_b32_e32 v40, 16, v116
	v_fma_f32 v42, v40, v40, v38
	v_fma_f32 v43, v41, v41, v39
	ds_read_b128 v[38:41], v1 offset:4096
	v_and_b32_e32 v45, 0xffff0000, v120
	v_and_b32_e32 v44, 0xffff0000, v116
	s_waitcnt lgkmcnt(1)
	v_mfma_f32_32x32x16_bf16 v[50:65], v[34:37], v[78:81], v[50:65]
	v_fma_f32 v34, v44, v44, v42
	v_fma_f32 v35, v45, v45, v43
	v_lshlrev_b32_e32 v37, 16, v121
	v_lshlrev_b32_e32 v36, 16, v117
	v_fma_f32 v42, v36, v36, v34
	v_fma_f32 v43, v37, v37, v35
	v_and_b32_e32 v45, 0xffff0000, v121
	ds_read_b128 v[34:37], v1 offset:5120
	v_and_b32_e32 v44, 0xffff0000, v117
	s_waitcnt lgkmcnt(1)
	v_mfma_f32_32x32x16_bf16 v[18:33], v[38:41], v[82:85], v[18:33]
	v_fma_f32 v38, v44, v44, v42
	v_fma_f32 v39, v45, v45, v43
	v_add_f32_e32 v38, v46, v38
	v_add_f32_e32 v42, v38, v39
	v_mul_f32_e64 v38, v166, v126
	v_mul_f32_e64 v39, v166, v127
	v_pk_mul_f32 v[14:15], v[38:39], v[14:15]
	ds_read_b128 v[38:41], v1 offset:6144
	v_cvt_pk_bf16_f32 v126, v14, v15
	v_pk_mul_f32 v[14:15], v[166:167], v[136:137] op_sel_hi:[0,1]
	v_pk_mul_f32 v[14:15], v[14:15], v[16:17]
	s_waitcnt lgkmcnt(1)
	v_mfma_f32_32x32x16_bf16 v[50:65], v[34:37], v[86:89], v[50:65]
	v_cvt_pk_bf16_f32 v127, v14, v15
	v_mul_f32_e64 v14, v166, v128
	v_mul_f32_e64 v15, v166, v129
	v_mul_f32_e64 v10, v14, v10
	v_mul_f32_e64 v11, v15, v11
	ds_read_b128 v[14:17], v1 offset:7168
	v_cvt_pk_bf16_f32 v128, v10, v11
	v_pk_mul_f32 v[10:11], v[166:167], v[134:135] op_sel_hi:[0,1]
	v_pk_mul_f32 v[10:11], v[10:11], v[12:13]
	s_waitcnt lgkmcnt(1)
	v_mfma_f32_32x32x16_bf16 v[18:33], v[38:41], v[90:93], v[18:33]
	v_cvt_pk_bf16_f32 v129, v10, v11
	v_mul_f32_e64 v10, v166, v130
	v_mul_f32_e64 v11, v166, v131
	v_mul_f32_e64 v6, v10, v6
	v_mul_f32_e64 v7, v11, v7
	ds_read_b128 v[10:13], v1 offset:8192
	v_cvt_pk_bf16_f32 v130, v6, v7
	v_pk_mul_f32 v[6:7], v[166:167], v[132:133] op_sel_hi:[0,1]
	v_pk_mul_f32 v[6:7], v[6:7], v[8:9]
	s_waitcnt lgkmcnt(1)
	v_mfma_f32_32x32x16_bf16 v[50:65], v[14:17], v[94:97], v[50:65]
	v_cvt_pk_bf16_f32 v131, v6, v7
	v_mul_f32_e64 v6, v166, v124
	v_mul_f32_e64 v7, v166, v125
	v_mul_f32_e64 v2, v6, v2
	v_mul_f32_e64 v3, v7, v3
	ds_read_b128 v[6:9], v1 offset:9216
	v_cvt_pk_bf16_f32 v132, v2, v3
	v_pk_mul_f32 v[2:3], v[166:167], v[122:123] op_sel_hi:[0,1]
	v_pk_mul_f32 v[2:3], v[2:3], v[4:5]
	s_waitcnt lgkmcnt(1)
	v_mfma_f32_32x32x16_bf16 v[18:33], v[10:13], v[98:101], v[18:33]
	v_cvt_pk_bf16_f32 v133, v2, v3
	ds_read_b128 v[2:5], v1 offset:10240
	v_lshlrev_b32_e32 v11, 16, v130
	v_lshlrev_b32_e32 v10, 16, v126
	v_lshlrev_b32_e32 v13, 16, v131
	v_lshlrev_b32_e32 v12, 16, v127
	s_waitcnt lgkmcnt(1)
	v_mfma_f32_32x32x16_bf16 v[50:65], v[6:9], v[102:105], v[50:65]
	v_and_b32_e32 v7, 0xffff0000, v130
	v_and_b32_e32 v6, 0xffff0000, v126
	v_mul_f32_e64 v6, v6, v6
	v_mul_f32_e64 v7, v7, v7
	v_fma_f32 v10, v10, v10, v6
	v_fma_f32 v11, v11, v11, v7
	ds_read_b128 v[6:9], v1 offset:11264
	s_waitcnt lgkmcnt(1)
	v_mfma_f32_32x32x16_bf16 v[18:33], v[2:5], v[106:109], v[18:33]
	v_fma_f32 v2, v12, v12, v10
	v_fma_f32 v3, v13, v13, v11
	v_and_b32_e32 v5, 0xffff0000, v131
	v_and_b32_e32 v4, 0xffff0000, v127
	v_fma_f32 v10, v4, v4, v2
	v_fma_f32 v11, v5, v5, v3
	ds_read_b128 v[2:5], v1 offset:12288
	v_lshlrev_b32_e32 v13, 16, v132
	v_lshlrev_b32_e32 v12, 16, v128
	s_waitcnt lgkmcnt(1)
	v_mfma_f32_32x32x16_bf16 v[50:65], v[6:9], v[110:113], v[50:65]
	v_fma_f32 v6, v12, v12, v10
	v_fma_f32 v7, v13, v13, v11
	v_and_b32_e32 v9, 0xffff0000, v132
	v_and_b32_e32 v8, 0xffff0000, v128
	v_fma_f32 v10, v8, v8, v6
	v_fma_f32 v11, v9, v9, v7
	ds_read_b128 v[6:9], v1 offset:13312
	v_lshlrev_b32_e32 v13, 16, v133
	v_lshlrev_b32_e32 v12, 16, v129
	s_waitcnt lgkmcnt(1)
	v_mfma_f32_32x32x16_bf16 v[18:33], v[2:5], v[114:117], v[18:33]
	v_fma_f32 v2, v12, v12, v10
	v_fma_f32 v3, v13, v13, v11
	v_and_b32_e32 v5, 0xffff0000, v133
	v_and_b32_e32 v4, 0xffff0000, v129
	v_fma_f32 v2, v4, v4, v2
	v_fma_f32 v3, v5, v5, v3
	v_add_f32_e32 v2, v42, v2
	v_add_f32_e32 v10, v2, v3
	s_waitcnt lgkmcnt(0)
	v_mfma_f32_32x32x16_bf16 v[50:65], v[6:9], v[118:121], v[50:65]
	ds_bpermute_b32 v6, v189, v10
	ds_read_b128 v[2:5], v1 offset:14336
	s_waitcnt lgkmcnt(1)
	v_add_f32_e32 v10, v10, v6
	ds_read_b128 v[6:9], v1 offset:15360
	s_waitcnt lgkmcnt(1)
	v_mfma_f32_32x32x16_bf16 v[18:33], v[2:5], v[126:129], v[18:33]
	v_lshl_add_u64 v[2:3], s[0:1], 0, v[190:191]
	s_waitcnt vmcnt(4)
	s_barrier
	global_load_lds_dwordx4 v[2:3], off
	ds_read_b128 v[2:5], v1 offset:16384
	v_mul_f32_e32 v38, v201, v10
	s_waitcnt lgkmcnt(1)
	v_mfma_f32_32x32x16_bf16 v[50:65], v[6:9], v[130:133], v[50:65]
	v_sqrt_f32_e32 v201, v38
	v_lshl_add_u64 v[6:7], s[0:1], 0, v[192:193]
	v_readfirstlane_b32 s0, v167
	s_mov_b32 m0, s0
	ds_read_b128 v[122:125], v1 offset:18432
	global_load_lds_dwordx4 v[6:7], off
	s_nop 5
	v_add_f32_e32 v18, v18, v50
	ds_read_b128 v[34:37], v1 offset:17408
	s_waitcnt lgkmcnt(2)
	v_mfma_f32_32x32x16_bf16 v[2:17], v[2:5], v[66:69], 0
	v_fmac_f32_e32 v18, 0xbf8020c5, v201
	v_mul_f32_e32 v18, 0x3db8aa3b, v18
	v_exp_f32_e32 v138, v18
	v_add_f32_e32 v18, v19, v51
	v_fmac_f32_e32 v18, 0xbf8020c5, v201
	v_mul_f32_e32 v18, 0x3db8aa3b, v18
	v_exp_f32_e32 v140, v18
	v_add_f32_e32 v18, v20, v52
	v_fmac_f32_e32 v18, 0xbf8020c5, v201
	v_mul_f32_e32 v18, 0x3db8aa3b, v18
	ds_read_b128 v[134:137], v1 offset:19456
	s_waitcnt lgkmcnt(2)
	v_mfma_f32_32x32x16_bf16 v[2:17], v[122:125], v[74:77], v[2:17]
	v_exp_f32_e32 v123, v18
	v_add_f32_e32 v50, v21, v53
	ds_read_b128 v[18:21], v1 offset:20480
	v_fmac_f32_e32 v50, 0xbf8020c5, v201
	v_add_f32_e32 v22, v22, v54
	v_mul_f32_e32 v50, 0x3db8aa3b, v50
	v_fmac_f32_e32 v22, 0xbf8020c5, v201
	s_waitcnt lgkmcnt(2)
	v_mfma_f32_32x32x16_bf16 v[34:49], v[34:37], v[70:73], 0
	v_exp_f32_e32 v124, v50
	v_mul_f32_e32 v22, 0x3db8aa3b, v22
	v_add_f32_e32 v139, 0, v138
	v_exp_f32_e32 v54, v22
	ds_read_b128 v[50:53], v1 offset:21504
	v_add_f32_e32 v23, v23, v55
	v_fmac_f32_e32 v23, 0xbf8020c5, v201
	s_waitcnt lgkmcnt(1)
	v_mfma_f32_32x32x16_bf16 v[2:17], v[18:21], v[82:85], v[2:17]
	v_add_f32_e32 v18, v140, v139
	v_add_f32_e32 v18, v123, v18
	v_add_f32_e32 v18, v124, v18
	v_add_f32_e32 v22, v54, v18
	ds_read_b128 v[18:21], v1 offset:22528
	v_mul_f32_e32 v23, 0x3db8aa3b, v23
	v_exp_f32_e32 v55, v23
	v_mfma_f32_32x32x16_bf16 v[34:49], v[134:137], v[78:81], v[34:49]
	v_add_f32_e32 v23, v24, v56
	v_fmac_f32_e32 v23, 0xbf8020c5, v201
	v_mul_f32_e32 v23, 0x3db8aa3b, v23
	v_exp_f32_e32 v56, v23
	v_add_f32_e32 v23, v26, v58
	v_fmac_f32_e32 v23, 0xbf8020c5, v201
	v_mul_f32_e32 v23, 0x3db8aa3b, v23
	s_waitcnt lgkmcnt(1)
	v_mfma_f32_32x32x16_bf16 v[34:49], v[50:53], v[86:89], v[34:49]
	ds_read_b128 v[50:53], v1 offset:23552
	v_exp_f32_e32 v58, v23
	v_add_f32_e32 v22, v55, v22
	v_add_f32_e32 v22, v56, v22
	s_add_u32 s0, s40, 0x14000
	s_addc_u32 s1, s41, 0
	s_mov_b32 m0, s54
	s_waitcnt lgkmcnt(1)
	v_mfma_f32_32x32x16_bf16 v[2:17], v[18:21], v[90:93], v[2:17]
	v_add_f32_e32 v18, v25, v57
	v_fmac_f32_e32 v18, 0xbf8020c5, v201
	v_mul_f32_e32 v18, 0x3db8aa3b, v18
	v_exp_f32_e32 v57, v18
	ds_read_b128 v[18:21], v1 offset:24576
	v_cvt_pk_bf16_f32 v122, v138, v140
	v_cvt_pk_bf16_f32 v123, v123, v124
	v_add_f32_e32 v22, v57, v22
	v_add_f32_e32 v26, v58, v22
	ds_read_b128 v[22:25], v1 offset:25600
	s_waitcnt lgkmcnt(2)
	v_mfma_f32_32x32x16_bf16 v[34:49], v[50:53], v[94:97], v[34:49]
	v_cvt_pk_bf16_f32 v124, v54, v55
	v_cvt_pk_bf16_f32 v125, v56, v57
	v_readfirstlane_b32 s54, v197
	s_waitcnt lgkmcnt(1)
	v_mfma_f32_32x32x16_bf16 v[2:17], v[18:21], v[98:101], v[2:17]
	v_add_f32_e32 v18, v27, v59
	v_fmac_f32_e32 v18, 0xbf8020c5, v201
	v_mul_f32_e32 v18, 0x3db8aa3b, v18
	v_exp_f32_e32 v59, v18
	v_add_f32_e32 v27, v28, v60
	ds_read_b128 v[18:21], v1 offset:26624
	v_fmac_f32_e32 v27, 0xbf8020c5, v201
	s_waitcnt lgkmcnt(1)
	v_mfma_f32_32x32x16_bf16 v[34:49], v[22:25], v[102:105], v[34:49]
	v_mul_f32_e32 v22, 0x3db8aa3b, v27
	v_exp_f32_e32 v60, v22
	v_add_f32_e32 v22, v29, v61
	v_fmac_f32_e32 v22, 0xbf8020c5, v201
	v_mul_f32_e32 v22, 0x3db8aa3b, v22
	v_exp_f32_e32 v61, v22
	ds_read_b128 v[22:25], v1 offset:27648
	s_waitcnt lgkmcnt(1)
	v_mfma_f32_32x32x16_bf16 v[2:17], v[18:21], v[106:109], v[2:17]
	v_add_f32_e32 v18, v59, v26
	v_add_f32_e32 v18, v60, v18
	v_add_f32_e32 v26, v61, v18
	v_add_f32_e32 v18, v30, v62
	v_fmac_f32_e32 v18, 0xbf8020c5, v201
	v_mul_f32_e32 v27, 0x3db8aa3b, v18
	ds_read_b128 v[18:21], v1 offset:28672
	s_waitcnt lgkmcnt(1)
	v_mfma_f32_32x32x16_bf16 v[34:49], v[22:25], v[110:113], v[34:49]
	v_add_f32_e32 v22, v31, v63
	v_fmac_f32_e32 v22, 0xbf8020c5, v201
	v_mul_f32_e32 v22, 0x3db8aa3b, v22
	v_exp_f32_e32 v145, v22
	ds_read_b128 v[22:25], v1 offset:29696
	v_exp_f32_e32 v144, v27
	v_add_f32_e32 v27, v32, v64
	v_fmac_f32_e32 v27, 0xbf8020c5, v201
	s_waitcnt lgkmcnt(1)
	v_mfma_f32_32x32x16_bf16 v[2:17], v[18:21], v[114:117], v[2:17]
	v_mul_f32_e32 v18, 0x3db8aa3b, v27
	v_exp_f32_e32 v146, v18
	v_add_f32_e32 v18, v33, v65
	v_fmac_f32_e32 v18, 0xbf8020c5, v201
	v_mul_f32_e32 v27, 0x3db8aa3b, v18
	v_exp_f32_e32 v147, v27
	ds_read_b128 v[18:21], v1 offset:30720
	s_waitcnt lgkmcnt(1)
	v_mfma_f32_32x32x16_bf16 v[34:49], v[22:25], v[118:121], v[34:49]
	v_add_f32_e32 v22, v144, v26
	v_add_f32_e32 v22, v145, v22
	v_add_f32_e32 v22, v146, v22
	v_add_f32_e32 v148, v147, v22
	ds_read_b128 v[22:25], v1 offset:31744
	s_waitcnt vmcnt(4)
	s_barrier
	s_waitcnt lgkmcnt(1)
	v_mfma_f32_32x32x16_bf16 v[2:17], v[18:21], v[126:129], v[2:17]
	v_lshl_add_u64 v[18:19], s[0:1], 0, v[190:191]
	global_load_lds_dwordx4 v[18:19], off
	ds_read_b128 v[18:21], v1 offset:32768
	ds_read_b128 v[136:139], v1 offset:34816
	v_cvt_pk_bf16_f32 v134, v58, v59
	v_cvt_pk_bf16_f32 v135, v60, v61
	s_waitcnt lgkmcnt(2)
	v_mfma_f32_32x32x16_bf16 v[34:49], v[22:25], v[130:133], v[34:49]
	v_lshl_add_u64 v[22:23], s[0:1], 0, v[192:193]
	v_readfirstlane_b32 s0, v199
	s_mov_b32 m0, s0
	s_add_u32 s0, s40, 0x18000
	global_load_lds_dwordx4 v[22:23], off
	ds_read_b128 v[50:53], v1 offset:33792
	s_nop 5
	v_add_f32_e32 v2, v2, v34
	v_fmac_f32_e32 v2, 0xbf8020c5, v201
	v_mul_f32_e32 v2, 0x3db8aa3b, v2
	v_exp_f32_e32 v149, v2
	v_add_f32_e32 v2, v3, v35
	v_fmac_f32_e32 v2, 0xbf8020c5, v201
	s_waitcnt lgkmcnt(2)
	v_mfma_f32_32x32x16_bf16 v[18:33], v[18:21], v[66:69], 0
	v_mul_f32_e32 v2, 0x3db8aa3b, v2
	v_exp_f32_e32 v150, v2
	ds_read_b128 v[140:143], v1 offset:35840
	v_add_f32_e32 v2, v148, v149
	v_add_f32_e32 v6, v6, v38
	v_add_f32_e32 v34, v150, v2
	v_add_f32_e32 v2, v4, v36
	s_waitcnt lgkmcnt(1)
	v_mfma_f32_32x32x16_bf16 v[50:65], v[50:53], v[70:73], 0
	v_fmac_f32_e32 v2, 0xbf8020c5, v201
	v_mul_f32_e32 v2, 0x3db8aa3b, v2
	v_fmac_f32_e32 v6, 0xbf8020c5, v201
	v_mul_f32_e32 v6, 0x3db8aa3b, v6
	v_exp_f32_e32 v38, v6
	v_add_f32_e32 v6, v8, v40
	v_fmac_f32_e32 v6, 0xbf8020c5, v201
	v_mfma_f32_32x32x16_bf16 v[18:33], v[136:139], v[74:77], v[18:33]
	v_cvt_pk_bf16_f32 v136, v144, v145
	v_cvt_pk_bf16_f32 v137, v146, v147
	ds_read_b128 v[144:147], v1 offset:36864
	v_exp_f32_e32 v139, v2
	v_add_f32_e32 v2, v5, v37
	v_fmac_f32_e32 v2, 0xbf8020c5, v201
	v_mul_f32_e32 v2, 0x3db8aa3b, v2
	s_waitcnt lgkmcnt(1)
	v_mfma_f32_32x32x16_bf16 v[50:65], v[140:143], v[78:81], v[50:65]
	v_exp_f32_e32 v140, v2
	ds_read_b128 v[2:5], v1 offset:37888
	v_add_f32_e32 v34, v139, v34
	v_mul_f32_e32 v6, 0x3db8aa3b, v6
	v_add_f32_e32 v138, v140, v34
	ds_read_b128 v[34:37], v1 offset:38912
	v_add_f32_e32 v10, v10, v42
	s_waitcnt lgkmcnt(2)
	v_mfma_f32_32x32x16_bf16 v[18:33], v[144:147], v[82:85], v[18:33]
	v_fmac_f32_e32 v10, 0xbf8020c5, v201
	s_addc_u32 s1, s41, 0
	s_mov_b32 m0, s54
	v_cvt_pk_bf16_f32 v139, v139, v140
	s_waitcnt lgkmcnt(1)
	v_mfma_f32_32x32x16_bf16 v[50:65], v[2:5], v[86:89], v[50:65]
	v_add_f32_e32 v2, v7, v39
	v_fmac_f32_e32 v2, 0xbf8020c5, v201
	v_mul_f32_e32 v2, 0x3db8aa3b, v2
	v_exp_f32_e32 v39, v2
	ds_read_b128 v[2:5], v1 offset:39936
	v_cvt_pk_bf16_f32 v140, v38, v39
	s_waitcnt lgkmcnt(1)
	v_mfma_f32_32x32x16_bf16 v[18:33], v[34:37], v[90:93], v[18:33]
	v_exp_f32_e32 v34, v6
	v_add_f32_e32 v6, v9, v41
	v_fmac_f32_e32 v6, 0xbf8020c5, v201
	v_mul_f32_e32 v6, 0x3db8aa3b, v6
	v_exp_f32_e32 v35, v6
	ds_read_b128 v[6:9], v1 offset:40960
	v_cvt_pk_bf16_f32 v141, v34, v35
	s_waitcnt lgkmcnt(1)
	v_mfma_f32_32x32x16_bf16 v[50:65], v[2:5], v[94:97], v[50:65]
	v_add_f32_e32 v2, v38, v138
	v_add_f32_e32 v2, v39, v2
	v_add_f32_e32 v2, v34, v2
	v_add_f32_e32 v36, v35, v2
	ds_read_b128 v[2:5], v1 offset:41984
	v_cvt_pk_bf16_f32 v138, v149, v150
	s_waitcnt lgkmcnt(1)
	v_mfma_f32_32x32x16_bf16 v[18:33], v[6:9], v[98:101], v[18:33]
	v_mul_f32_e32 v6, 0x3db8aa3b, v10
	v_exp_f32_e32 v10, v6
	v_add_f32_e32 v6, v11, v43
	v_fmac_f32_e32 v6, 0xbf8020c5, v201
	v_mul_f32_e32 v6, 0x3db8aa3b, v6
	v_exp_f32_e32 v11, v6
	ds_read_b128 v[6:9], v1 offset:43008
	s_waitcnt lgkmcnt(1)
	v_mfma_f32_32x32x16_bf16 v[50:65], v[2:5], v[102:105], v[50:65]
	v_add_f32_e32 v2, v10, v36
	v_add_f32_e32 v36, v11, v2
	v_add_f32_e32 v2, v12, v44
	v_fmac_f32_e32 v2, 0xbf8020c5, v201
	v_mul_f32_e32 v2, 0x3db8aa3b, v2
	v_exp_f32_e32 v40, v2
	ds_read_b128 v[2:5], v1 offset:44032
	v_add_f32_e32 v12, v14, v46
	v_fmac_f32_e32 v12, 0xbf8020c5, v201
	s_waitcnt lgkmcnt(0)
	v_mfma_f32_32x32x16_bf16 v[50:65], v[2:5], v[110:113], v[50:65]
	v_mul_f32_e32 v2, 0x3db8aa3b, v12
	v_exp_f32_e32 v42, v2
	v_add_f32_e32 v2, v15, v47
	v_fmac_f32_e32 v2, 0xbf8020c5, v201
	v_mul_f32_e32 v2, 0x3db8aa3b, v2
	v_exp_f32_e32 v43, v2
	ds_read_b128 v[2:5], v1 offset:46080
	v_mfma_f32_32x32x16_bf16 v[18:33], v[6:9], v[106:109], v[18:33]
	v_add_f32_e32 v6, v13, v45
	v_fmac_f32_e32 v6, 0xbf8020c5, v201
	v_mul_f32_e32 v6, 0x3db8aa3b, v6
	v_exp_f32_e32 v41, v6
	ds_read_b128 v[6:9], v1 offset:45056
	v_add_f32_e32 v13, v16, v48
	v_fmac_f32_e32 v13, 0xbf8020c5, v201
	s_waitcnt lgkmcnt(1)
	v_mfma_f32_32x32x16_bf16 v[50:65], v[2:5], v[118:121], v[50:65]
	v_mul_f32_e32 v2, 0x3db8aa3b, v13
	v_exp_f32_e32 v44, v2
	v_add_f32_e32 v2, v17, v49
	v_fmac_f32_e32 v2, 0xbf8020c5, v201
	v_mul_f32_e32 v2, 0x3db8aa3b, v2
	v_exp_f32_e32 v45, v2
	ds_read_b128 v[2:5], v1 offset:48128
	s_waitcnt lgkmcnt(1)
	v_mfma_f32_32x32x16_bf16 v[18:33], v[6:9], v[114:117], v[18:33]
	v_add_f32_e32 v6, v40, v36
	v_add_f32_e32 v6, v41, v6
	v_add_f32_e32 v6, v42, v6
	v_add_f32_e32 v12, v43, v6
	ds_read_b128 v[6:9], v1 offset:47104
	s_waitcnt vmcnt(4)
	s_barrier
	s_waitcnt lgkmcnt(0)
	v_mfma_f32_32x32x16_bf16 v[18:33], v[6:9], v[126:129], v[18:33]
	v_add_f32_e32 v6, v44, v12
	v_add_f32_e32 v46, v45, v6
	v_cvt_pk_bf16_f32 v142, v10, v11
	v_cvt_pk_bf16_f32 v143, v40, v41
	v_cvt_pk_bf16_f32 v144, v42, v43
	v_cvt_pk_bf16_f32 v145, v44, v45
	v_mfma_f32_32x32x16_bf16 v[50:65], v[2:5], v[130:133], v[50:65]
	v_lshl_add_u64 v[2:3], s[0:1], 0, v[190:191]
	global_load_lds_dwordx4 v[2:3], off
	ds_read_b128 v[2:5], v1 offset:49152
	ds_read_b128 v[146:149], v1 offset:51200
	s_nop 7
	v_add_f32_e32 v6, v18, v50
	v_fmac_f32_e32 v6, 0xbf8020c5, v201
	v_mul_f32_e32 v6, 0x3db8aa3b, v6
	v_exp_f32_e32 v150, v6
	v_lshl_add_u64 v[6:7], s[0:1], 0, v[192:193]
	v_readfirstlane_b32 s0, v198
	s_mov_b32 m0, s0
	v_add_f32_e32 v19, v19, v51
	global_load_lds_dwordx4 v[6:7], off
	v_fmac_f32_e32 v19, 0xbf8020c5, v201
	ds_read_b128 v[34:37], v1 offset:50176
	s_waitcnt lgkmcnt(2)
	v_mfma_f32_32x32x16_bf16 v[2:17], v[2:5], v[66:69], 0
	v_mul_f32_e32 v19, 0x3db8aa3b, v19
	v_exp_f32_e32 v153, v19
	v_add_f32_e32 v19, v20, v52
	v_fmac_f32_e32 v19, 0xbf8020c5, v201
	v_mul_f32_e32 v19, 0x3db8aa3b, v19
	v_exp_f32_e32 v158, v19
	v_add_f32_e32 v18, v46, v150
	v_add_f32_e32 v18, v153, v18
	ds_read_b128 v[154:157], v1 offset:52224
	s_waitcnt lgkmcnt(2)
	v_mfma_f32_32x32x16_bf16 v[2:17], v[146:149], v[74:77], v[2:17]
	v_add_f32_e32 v146, v158, v18
	v_add_f32_e32 v18, v21, v53
	v_fmac_f32_e32 v18, 0xbf8020c5, v201
	v_mul_f32_e32 v18, 0x3db8aa3b, v18
	v_exp_f32_e32 v147, v18
	ds_read_b128 v[18:21], v1 offset:53248
	ds_read_b128 v[50:53], v1 offset:54272
	s_waitcnt lgkmcnt(3)
	v_mfma_f32_32x32x16_bf16 v[34:49], v[34:37], v[70:73], 0
	v_add_f32_e32 v22, v22, v54
	v_fmac_f32_e32 v22, 0xbf8020c5, v201
	v_mul_f32_e32 v22, 0x3db8aa3b, v22
	v_exp_f32_e32 v54, v22
	v_add_f32_e32 v22, v23, v55
	v_fmac_f32_e32 v22, 0xbf8020c5, v201
	v_add_f32_e32 v28, v28, v60
	s_waitcnt lgkmcnt(1)
	v_mfma_f32_32x32x16_bf16 v[2:17], v[18:21], v[82:85], v[2:17]
	v_mul_f32_e32 v18, 0x3db8aa3b, v22
	v_exp_f32_e32 v55, v18
	v_add_f32_e32 v18, v24, v56
	v_fmac_f32_e32 v18, 0xbf8020c5, v201
	v_mul_f32_e32 v18, 0x3db8aa3b, v18
	v_exp_f32_e32 v56, v18
	ds_read_b128 v[18:21], v1 offset:55296
	v_mfma_f32_32x32x16_bf16 v[34:49], v[154:157], v[78:81], v[34:49]
	v_add_f32_e32 v22, v147, v146
	v_add_f32_e32 v22, v54, v22
	v_add_f32_e32 v22, v55, v22
	v_fmac_f32_e32 v28, 0xbf8020c5, v201
	v_add_f32_e32 v30, v30, v62
	v_fmac_f32_e32 v30, 0xbf8020c5, v201
	s_add_u32 s0, s40, 0x1c000
	s_waitcnt lgkmcnt(1)
	v_mfma_f32_32x32x16_bf16 v[34:49], v[50:53], v[86:89], v[34:49]
	v_add_f32_e32 v51, v25, v57
	v_fmac_f32_e32 v51, 0xbf8020c5, v201
	v_add_f32_e32 v50, v56, v22
	ds_read_b128 v[22:25], v1 offset:56320
	s_addc_u32 s1, s41, 0
	v_readfirstlane_b32 s40, v151
	s_mov_b32 m0, s40
	s_waitcnt lgkmcnt(1)
	v_mfma_f32_32x32x16_bf16 v[2:17], v[18:21], v[90:93], v[2:17]
	v_mul_f32_e32 v18, 0x3db8aa3b, v51
	v_exp_f32_e32 v51, v18
	v_add_f32_e32 v18, v26, v58
	v_fmac_f32_e32 v18, 0xbf8020c5, v201
	v_mul_f32_e32 v18, 0x3db8aa3b, v18
	v_exp_f32_e32 v26, v18
	ds_read_b128 v[18:21], v1 offset:57344
	s_waitcnt lgkmcnt(1)
	v_mfma_f32_32x32x16_bf16 v[34:49], v[22:25], v[94:97], v[34:49]
	v_add_f32_e32 v22, v27, v59
	v_fmac_f32_e32 v22, 0xbf8020c5, v201
	v_mul_f32_e32 v22, 0x3db8aa3b, v22
	v_exp_f32_e32 v27, v22
	ds_read_b128 v[22:25], v1 offset:58368
	v_cvt_pk_bf16_f32 v146, v150, v153
	v_cvt_pk_bf16_f32 v149, v56, v51
	s_waitcnt lgkmcnt(1)
	v_mfma_f32_32x32x16_bf16 v[2:17], v[18:21], v[98:101], v[2:17]
	v_mul_f32_e32 v18, 0x3db8aa3b, v28
	v_exp_f32_e32 v28, v18
	v_add_f32_e32 v18, v51, v50
	v_add_f32_e32 v18, v26, v18
	v_add_f32_e32 v18, v27, v18
	v_add_f32_e32 v50, v28, v18
	ds_read_b128 v[18:21], v1 offset:59392
	s_waitcnt lgkmcnt(1)
	v_mfma_f32_32x32x16_bf16 v[34:49], v[22:25], v[102:105], v[34:49]
	v_add_f32_e32 v22, v29, v61
	v_fmac_f32_e32 v22, 0xbf8020c5, v201
	v_mul_f32_e32 v22, 0x3db8aa3b, v22
	v_exp_f32_e32 v29, v22
	ds_read_b128 v[22:25], v1 offset:60416
	v_cvt_pk_bf16_f32 v150, v26, v27
	v_cvt_pk_bf16_f32 v147, v158, v147
	s_waitcnt lgkmcnt(1)
	v_mfma_f32_32x32x16_bf16 v[2:17], v[18:21], v[106:109], v[2:17]
	v_mul_f32_e32 v18, 0x3db8aa3b, v30
	v_exp_f32_e32 v57, v18
	v_add_f32_e32 v18, v31, v63
	v_fmac_f32_e32 v18, 0xbf8020c5, v201
	v_mul_f32_e32 v18, 0x3db8aa3b, v18
	v_exp_f32_e32 v58, v18
	ds_read_b128 v[18:21], v1 offset:61440
	s_waitcnt lgkmcnt(1)
	v_mfma_f32_32x32x16_bf16 v[34:49], v[22:25], v[110:113], v[34:49]
	v_add_f32_e32 v22, v29, v50
	v_add_f32_e32 v22, v57, v22
	v_add_f32_e32 v30, v58, v22
	v_add_f32_e32 v22, v32, v64
	v_fmac_f32_e32 v22, 0xbf8020c5, v201
	v_mul_f32_e32 v31, 0x3db8aa3b, v22
	ds_read_b128 v[22:25], v1 offset:62464
	s_waitcnt lgkmcnt(1)
	v_mfma_f32_32x32x16_bf16 v[2:17], v[18:21], v[114:117], v[2:17]
	v_add_f32_e32 v18, v33, v65
	v_fmac_f32_e32 v18, 0xbf8020c5, v201
	v_mul_f32_e32 v18, 0x3db8aa3b, v18
	v_exp_f32_e32 v60, v18
	ds_read_b128 v[18:21], v1 offset:63488
	v_exp_f32_e32 v59, v31
	v_cvt_pk_bf16_f32 v151, v28, v29
	s_waitcnt lgkmcnt(1)
	v_mfma_f32_32x32x16_bf16 v[34:49], v[22:25], v[118:121], v[34:49]
	ds_read_b128 v[22:25], v1 offset:64512
	s_waitcnt vmcnt(4)
	s_barrier
	v_add_f32_e32 v30, v59, v30
	v_add_f32_e32 v162, v60, v30
	v_cvt_pk_bf16_f32 v148, v54, v55
	v_cvt_pk_bf16_f32 v153, v59, v60
	s_waitcnt lgkmcnt(1)
	v_mfma_f32_32x32x16_bf16 v[2:17], v[18:21], v[126:129], v[2:17]
	v_lshl_add_u64 v[18:19], s[0:1], 0, v[190:191]
	global_load_lds_dwordx4 v[18:19], off
	ds_read_b128 v[18:21], v1
	ds_read_b128 v[154:157], v1 offset:2048
	v_readfirstlane_b32 s40, v200
	s_waitcnt lgkmcnt(2)
	v_mfma_f32_32x32x16_bf16 v[34:49], v[22:25], v[130:133], v[34:49]
	v_lshl_add_u64 v[22:23], s[0:1], 0, v[192:193]
	v_readfirstlane_b32 s0, v152
	s_mov_b32 m0, s0
	v_cvt_pk_bf16_f32 v152, v57, v58
	global_load_lds_dwordx4 v[22:23], off
	ds_read_b128 v[50:53], v1 offset:1024
	s_nop 5
	v_add_f32_e32 v2, v2, v34
	s_waitcnt lgkmcnt(2)
	v_mfma_f32_32x32x16_bf16 v[18:33], v[18:21], v[66:69], 0
	v_fmac_f32_e32 v2, 0xbf8020c5, v201
	v_mul_f32_e32 v2, 0x3db8aa3b, v2
	v_exp_f32_e32 v163, v2
	v_add_f32_e32 v2, v3, v35
	v_fmac_f32_e32 v2, 0xbf8020c5, v201
	v_mul_f32_e32 v2, 0x3db8aa3b, v2
	v_exp_f32_e32 v164, v2
	v_add_f32_e32 v2, v4, v36
	v_fmac_f32_e32 v2, 0xbf8020c5, v201
	v_mul_f32_e32 v2, 0x3db8aa3b, v2
	ds_read_b128 v[158:161], v1 offset:3072
	s_waitcnt lgkmcnt(2)
	v_mfma_f32_32x32x16_bf16 v[18:33], v[154:157], v[74:77], v[18:33]
	v_exp_f32_e32 v155, v2
	v_add_f32_e32 v2, v5, v37
	v_fmac_f32_e32 v2, 0xbf8020c5, v201
	v_mul_f32_e32 v2, 0x3db8aa3b, v2
	v_exp_f32_e32 v156, v2
	ds_read_b128 v[2:5], v1 offset:4096
	v_add_f32_e32 v34, v162, v163
	s_waitcnt lgkmcnt(2)
	v_mfma_f32_32x32x16_bf16 v[50:65], v[50:53], v[70:73], 0
	v_add_f32_e32 v34, v164, v34
	v_add_f32_e32 v6, v6, v38
	v_add_f32_e32 v34, v155, v34
	v_fmac_f32_e32 v6, 0xbf8020c5, v201
	v_add_f32_e32 v154, v156, v34
	ds_read_b128 v[34:37], v1 offset:5120
	v_readfirstlane_b32 s0, v196
	s_waitcnt lgkmcnt(1)
	v_mfma_f32_32x32x16_bf16 v[18:33], v[2:5], v[82:85], v[18:33]
	v_mul_f32_e32 v2, 0x3db8aa3b, v6
	v_exp_f32_e32 v38, v2
	v_add_f32_e32 v2, v7, v39
	v_fmac_f32_e32 v2, 0xbf8020c5, v201
	v_mul_f32_e32 v2, 0x3db8aa3b, v2
	v_exp_f32_e32 v39, v2
	ds_read_b128 v[2:5], v1 offset:6144
	v_mfma_f32_32x32x16_bf16 v[50:65], v[158:161], v[78:81], v[50:65]
	v_add_f32_e32 v6, v38, v154
	v_add_f32_e32 v154, v39, v6
	v_add_f32_e32 v6, v8, v40
	v_fmac_f32_e32 v6, 0xbf8020c5, v201
	v_mul_f32_e32 v6, 0x3db8aa3b, v6
	v_exp_f32_e32 v40, v6
	v_add_f32_e32 v6, v10, v42
	s_waitcnt lgkmcnt(1)
	v_mfma_f32_32x32x16_bf16 v[50:65], v[34:37], v[86:89], v[50:65]
	ds_read_b128 v[34:37], v1 offset:7168
	v_fmac_f32_e32 v6, 0xbf8020c5, v201
	v_mul_f32_e32 v6, 0x3db8aa3b, v6
	v_exp_f32_e32 v42, v6
	v_add_f32_e32 v6, v11, v43
	v_fmac_f32_e32 v6, 0xbf8020c5, v201
	v_mul_f32_e32 v6, 0x3db8aa3b, v6
	s_waitcnt lgkmcnt(1)
	v_mfma_f32_32x32x16_bf16 v[18:33], v[2:5], v[90:93], v[18:33]
	v_add_f32_e32 v2, v9, v41
	v_fmac_f32_e32 v2, 0xbf8020c5, v201
	v_mul_f32_e32 v2, 0x3db8aa3b, v2
	v_exp_f32_e32 v41, v2
	ds_read_b128 v[2:5], v1 offset:8192
	v_exp_f32_e32 v43, v6
	ds_read_b128 v[6:9], v1 offset:9216
	s_waitcnt lgkmcnt(2)
	v_mfma_f32_32x32x16_bf16 v[50:65], v[34:37], v[94:97], v[50:65]
	v_add_f32_e32 v11, v12, v44
	v_fmac_f32_e32 v11, 0xbf8020c5, v201
	s_mov_b32 m0, s0
	v_readfirstlane_b32 s0, v167
	v_cvt_pk_bf16_f32 v155, v155, v156
	v_cvt_pk_bf16_f32 v156, v38, v39
	v_cvt_pk_bf16_f32 v157, v40, v41
	s_waitcnt lgkmcnt(1)
	v_mfma_f32_32x32x16_bf16 v[18:33], v[2:5], v[98:101], v[18:33]
	v_add_f32_e32 v2, v40, v154
	v_add_f32_e32 v2, v41, v2
	v_add_f32_e32 v2, v42, v2
	v_add_f32_e32 v10, v43, v2
	ds_read_b128 v[2:5], v1 offset:10240
	v_cvt_pk_bf16_f32 v154, v163, v164
	v_cvt_pk_bf16_f32 v158, v42, v43
	s_waitcnt lgkmcnt(1)
	v_mfma_f32_32x32x16_bf16 v[50:65], v[6:9], v[102:105], v[50:65]
	v_mul_f32_e32 v6, 0x3db8aa3b, v11
	v_exp_f32_e32 v159, v6
	v_add_f32_e32 v6, v13, v45
	v_fmac_f32_e32 v6, 0xbf8020c5, v201
	v_mul_f32_e32 v6, 0x3db8aa3b, v6
	v_exp_f32_e32 v160, v6
	ds_read_b128 v[6:9], v1 offset:11264
	s_waitcnt lgkmcnt(1)
	v_mfma_f32_32x32x16_bf16 v[18:33], v[2:5], v[106:109], v[18:33]
	v_add_f32_e32 v2, v159, v10
	v_add_f32_e32 v10, v160, v2
	v_add_f32_e32 v2, v14, v46
	v_fmac_f32_e32 v2, 0xbf8020c5, v201
	v_mul_f32_e32 v2, 0x3db8aa3b, v2
	v_exp_f32_e32 v161, v2
	ds_read_b128 v[2:5], v1 offset:12288
	s_waitcnt lgkmcnt(1)
	v_mfma_f32_32x32x16_bf16 v[50:65], v[6:9], v[110:113], v[50:65]
	v_add_f32_e32 v6, v15, v47
	v_fmac_f32_e32 v6, 0xbf8020c5, v201
	v_mul_f32_e32 v6, 0x3db8aa3b, v6
	v_exp_f32_e32 v166, v6
	ds_read_b128 v[6:9], v1 offset:13312
	v_add_f32_e32 v11, v16, v48
	v_fmac_f32_e32 v11, 0xbf8020c5, v201
	s_waitcnt lgkmcnt(1)
	v_mfma_f32_32x32x16_bf16 v[18:33], v[2:5], v[114:117], v[18:33]
	v_mul_f32_e32 v2, 0x3db8aa3b, v11
	v_exp_f32_e32 v168, v2
	v_add_f32_e32 v2, v17, v49
	v_fmac_f32_e32 v2, 0xbf8020c5, v201
	v_mul_f32_e32 v2, 0x3db8aa3b, v2
	v_exp_f32_e32 v169, v2
	ds_read_b128 v[2:5], v1 offset:14336
	s_waitcnt lgkmcnt(1)
	v_mfma_f32_32x32x16_bf16 v[50:65], v[6:9], v[118:121], v[50:65]
	v_add_f32_e32 v6, v161, v10
	v_add_f32_e32 v6, v166, v6
	v_add_f32_e32 v6, v168, v6
	v_add_f32_e32 v170, v169, v6
	ds_read_b128 v[6:9], v1 offset:15360
	v_lshl_add_u64 v[10:11], s[42:43], 0, v[190:191]
	s_waitcnt vmcnt(4)
	s_waitcnt lgkmcnt(1)
	v_mfma_f32_32x32x16_bf16 v[18:33], v[2:5], v[126:129], v[18:33]
	s_barrier
	global_load_lds_dwordx4 v[10:11], off
	s_mov_b32 m0, s0
	ds_read_b128 v[2:5], v1 offset:16384
	ds_read_b128 v[162:165], v1 offset:18432
	v_cvt_pk_bf16_f32 v159, v159, v160
	s_waitcnt lgkmcnt(2)
	v_mfma_f32_32x32x16_bf16 v[50:65], v[6:9], v[130:133], v[50:65]
	v_lshl_add_u64 v[6:7], v[10:11], 0, s[58:59]
	global_load_lds_dwordx4 v[6:7], off
	ds_read_b128 v[34:37], v1 offset:17408
	v_cvt_pk_bf16_f32 v160, v161, v166
	v_cvt_pk_bf16_f32 v161, v168, v169
	ds_read_b128 v[166:169], v1 offset:19456
	s_nop 5
	v_add_f32_e32 v18, v18, v50
	v_fmac_f32_e32 v18, 0xbf8020c5, v201
	v_mul_f32_e32 v18, 0x3db8aa3b, v18
	v_exp_f32_e32 v171, v18
	v_add_f32_e32 v19, v19, v51
	v_fmac_f32_e32 v19, 0xbf8020c5, v201
	s_waitcnt lgkmcnt(1)
	v_mfma_f32_32x32x16_bf16 v[34:49], v[34:37], v[70:73], 0
	v_mul_f32_e32 v19, 0x3db8aa3b, v19
	v_add_f32_e32 v18, v170, v171
	v_exp_f32_e32 v170, v19
	v_add_f32_e32 v19, v20, v52
	v_fmac_f32_e32 v19, 0xbf8020c5, v201
	v_mul_f32_e32 v19, 0x3db8aa3b, v19
	v_exp_f32_e32 v172, v19
	v_mfma_f32_32x32x16_bf16 v[2:17], v[2:5], v[66:69], 0
	v_add_f32_e32 v18, v170, v18
	v_add_f32_e32 v22, v22, v54
	v_fmac_f32_e32 v22, 0xbf8020c5, v201
	v_mul_f32_e32 v22, 0x3db8aa3b, v22
	v_exp_f32_e32 v54, v22
	v_add_f32_e32 v22, v23, v55
	v_fmac_f32_e32 v22, 0xbf8020c5, v201
	s_waitcnt lgkmcnt(0)
	v_mfma_f32_32x32x16_bf16 v[34:49], v[166:169], v[78:81], v[34:49]
	v_add_f32_e32 v166, v172, v18
	v_add_f32_e32 v18, v21, v53
	v_fmac_f32_e32 v18, 0xbf8020c5, v201
	v_mul_f32_e32 v18, 0x3db8aa3b, v18
	v_exp_f32_e32 v167, v18
	ds_read_b128 v[18:21], v1 offset:21504
	ds_read_b128 v[50:53], v1 offset:22528
	v_mfma_f32_32x32x16_bf16 v[2:17], v[162:165], v[74:77], v[2:17]
	ds_read_b128 v[162:165], v1 offset:20480
	v_add_f32_e32 v28, v28, v60
	v_fmac_f32_e32 v28, 0xbf8020c5, v201
	v_add_f32_e32 v30, v30, v62
	v_fmac_f32_e32 v30, 0xbf8020c5, v201
	s_add_u32 s0, s42, 0x4000
	s_addc_u32 s1, s43, 0
	s_waitcnt lgkmcnt(2)
	v_mfma_f32_32x32x16_bf16 v[34:49], v[18:21], v[86:89], v[34:49]
	v_mul_f32_e32 v18, 0x3db8aa3b, v22
	v_exp_f32_e32 v55, v18
	v_add_f32_e32 v18, v24, v56
	v_fmac_f32_e32 v18, 0xbf8020c5, v201
	v_mul_f32_e32 v18, 0x3db8aa3b, v18
	v_exp_f32_e32 v56, v18
	ds_read_b128 v[18:21], v1 offset:23552
	s_waitcnt lgkmcnt(1)
	v_mfma_f32_32x32x16_bf16 v[2:17], v[162:165], v[82:85], v[2:17]
	v_add_f32_e32 v22, v167, v166
	v_add_f32_e32 v22, v54, v22
	v_add_f32_e32 v22, v55, v22
	s_mov_b32 m0, s40
	v_cvt_pk_bf16_f32 v162, v171, v170
	v_cvt_pk_bf16_f32 v163, v172, v167
	v_cvt_pk_bf16_f32 v164, v54, v55
	v_mfma_f32_32x32x16_bf16 v[2:17], v[50:53], v[90:93], v[2:17]
	v_add_f32_e32 v51, v25, v57
	v_fmac_f32_e32 v51, 0xbf8020c5, v201
	v_add_f32_e32 v50, v56, v22
	ds_read_b128 v[22:25], v1 offset:24576
	v_readfirstlane_b32 s40, v197
	s_waitcnt lgkmcnt(1)
	v_mfma_f32_32x32x16_bf16 v[34:49], v[18:21], v[94:97], v[34:49]
	v_mul_f32_e32 v18, 0x3db8aa3b, v51
	v_exp_f32_e32 v51, v18
	v_add_f32_e32 v18, v26, v58
	v_fmac_f32_e32 v18, 0xbf8020c5, v201
	v_mul_f32_e32 v18, 0x3db8aa3b, v18
	v_exp_f32_e32 v26, v18
	ds_read_b128 v[18:21], v1 offset:25600
	s_waitcnt lgkmcnt(1)
	v_mfma_f32_32x32x16_bf16 v[2:17], v[22:25], v[98:101], v[2:17]
	v_add_f32_e32 v22, v27, v59
	v_fmac_f32_e32 v22, 0xbf8020c5, v201
	v_mul_f32_e32 v22, 0x3db8aa3b, v22
	v_exp_f32_e32 v27, v22
	ds_read_b128 v[22:25], v1 offset:26624
	v_cvt_pk_bf16_f32 v165, v56, v51
	v_cvt_pk_bf16_f32 v166, v26, v27
	s_waitcnt lgkmcnt(1)
	v_mfma_f32_32x32x16_bf16 v[34:49], v[18:21], v[102:105], v[34:49]
	v_mul_f32_e32 v18, 0x3db8aa3b, v28
	v_exp_f32_e32 v28, v18
	v_add_f32_e32 v18, v51, v50
	v_add_f32_e32 v18, v26, v18
	v_add_f32_e32 v18, v27, v18
	v_add_f32_e32 v50, v28, v18
	ds_read_b128 v[18:21], v1 offset:27648
	s_waitcnt lgkmcnt(1)
	v_mfma_f32_32x32x16_bf16 v[2:17], v[22:25], v[106:109], v[2:17]
	v_add_f32_e32 v22, v29, v61
	v_fmac_f32_e32 v22, 0xbf8020c5, v201
	v_mul_f32_e32 v22, 0x3db8aa3b, v22
	v_exp_f32_e32 v29, v22
	ds_read_b128 v[22:25], v1 offset:28672
	v_cvt_pk_bf16_f32 v167, v28, v29
	s_waitcnt lgkmcnt(1)
	v_mfma_f32_32x32x16_bf16 v[34:49], v[18:21], v[110:113], v[34:49]
	v_mul_f32_e32 v18, 0x3db8aa3b, v30
	v_exp_f32_e32 v168, v18
	v_add_f32_e32 v18, v31, v63
	v_fmac_f32_e32 v18, 0xbf8020c5, v201
	v_mul_f32_e32 v18, 0x3db8aa3b, v18
	v_exp_f32_e32 v169, v18
	ds_read_b128 v[18:21], v1 offset:29696
	s_waitcnt lgkmcnt(1)
	v_mfma_f32_32x32x16_bf16 v[2:17], v[22:25], v[114:117], v[2:17]
	v_add_f32_e32 v22, v29, v50
	v_add_f32_e32 v22, v168, v22
	v_add_f32_e32 v30, v169, v22
	v_add_f32_e32 v22, v32, v64
	v_fmac_f32_e32 v22, 0xbf8020c5, v201
	v_mul_f32_e32 v31, 0x3db8aa3b, v22
	ds_read_b128 v[22:25], v1 offset:30720
	s_waitcnt lgkmcnt(1)
	v_mfma_f32_32x32x16_bf16 v[34:49], v[18:21], v[118:121], v[34:49]
	v_add_f32_e32 v18, v33, v65
	v_fmac_f32_e32 v18, 0xbf8020c5, v201
	v_mul_f32_e32 v18, 0x3db8aa3b, v18
	v_exp_f32_e32 v175, v18
	ds_read_b128 v[18:21], v1 offset:31744
	s_waitcnt vmcnt(4)
	s_barrier
	s_waitcnt lgkmcnt(1)
	v_mfma_f32_32x32x16_bf16 v[2:17], v[22:25], v[126:129], v[2:17]
	v_exp_f32_e32 v174, v31
	v_lshl_add_u64 v[22:23], s[0:1], 0, v[192:193]
	v_cvt_pk_bf16_f32 v168, v168, v169
	v_add_f32_e32 v30, v174, v30
	v_add_f32_e32 v176, v175, v30
	v_cvt_pk_bf16_f32 v169, v174, v175
	s_waitcnt lgkmcnt(0)
	v_mfma_f32_32x32x16_bf16 v[34:49], v[18:21], v[130:133], v[34:49]
	v_lshl_add_u64 v[18:19], s[0:1], 0, v[190:191]
	global_load_lds_dwordx4 v[18:19], off
	ds_read_b128 v[18:21], v1 offset:32768
	v_readfirstlane_b32 s0, v199
	s_mov_b32 m0, s0
	ds_read_b128 v[170:173], v1 offset:34816
	s_nop 5
	v_add_f32_e32 v2, v2, v34
	v_fmac_f32_e32 v2, 0xbf8020c5, v201
	v_mul_f32_e32 v2, 0x3db8aa3b, v2
	v_exp_f32_e32 v199, v2
	v_add_f32_e32 v2, v3, v35
	global_load_lds_dwordx4 v[22:23], off
	v_fmac_f32_e32 v2, 0xbf8020c5, v201
	ds_read_b128 v[50:53], v1 offset:33792
	s_waitcnt lgkmcnt(2)
	v_mfma_f32_32x32x16_bf16 v[18:33], v[18:21], v[66:69], 0
	v_mul_f32_e32 v2, 0x3db8aa3b, v2
	v_exp_f32_e32 v200, v2
	v_add_f32_e32 v2, v176, v199
	ds_read_b128 v[174:177], v1 offset:35840
	v_add_f32_e32 v6, v6, v38
	v_add_f32_e32 v34, v200, v2
	v_add_f32_e32 v2, v4, v36
	v_fmac_f32_e32 v2, 0xbf8020c5, v201
	v_mul_f32_e32 v2, 0x3db8aa3b, v2
	s_waitcnt lgkmcnt(2)
	v_mfma_f32_32x32x16_bf16 v[18:33], v[170:173], v[74:77], v[18:33]
	v_exp_f32_e32 v171, v2
	v_add_f32_e32 v2, v5, v37
	v_fmac_f32_e32 v2, 0xbf8020c5, v201
	v_mul_f32_e32 v2, 0x3db8aa3b, v2
	v_exp_f32_e32 v172, v2
	ds_read_b128 v[2:5], v1 offset:36864
	v_add_f32_e32 v34, v171, v34
	s_waitcnt lgkmcnt(2)
	v_mfma_f32_32x32x16_bf16 v[50:65], v[50:53], v[70:73], 0
	v_add_f32_e32 v170, v172, v34
	ds_read_b128 v[34:37], v1 offset:37888
	v_fmac_f32_e32 v6, 0xbf8020c5, v201
	v_mul_f32_e32 v6, 0x3db8aa3b, v6
	v_exp_f32_e32 v38, v6
	v_add_f32_e32 v6, v8, v40
	v_fmac_f32_e32 v6, 0xbf8020c5, v201
	s_waitcnt lgkmcnt(2)
	v_mfma_f32_32x32x16_bf16 v[50:65], v[174:177], v[78:81], v[50:65]
	v_mul_f32_e32 v6, 0x3db8aa3b, v6
	v_add_f32_e32 v10, v10, v42
	v_fmac_f32_e32 v10, 0xbf8020c5, v201
	s_add_u32 s0, s42, 0x8000
	s_addc_u32 s1, s43, 0
	s_mov_b32 m0, s40
	v_cvt_pk_bf16_f32 v171, v171, v172
	s_waitcnt lgkmcnt(1)
	v_mfma_f32_32x32x16_bf16 v[18:33], v[2:5], v[82:85], v[18:33]
	v_add_f32_e32 v2, v7, v39
	v_fmac_f32_e32 v2, 0xbf8020c5, v201
	v_mul_f32_e32 v2, 0x3db8aa3b, v2
	v_exp_f32_e32 v39, v2
	ds_read_b128 v[2:5], v1 offset:38912
	v_cvt_pk_bf16_f32 v172, v38, v39
	s_waitcnt lgkmcnt(1)
	v_mfma_f32_32x32x16_bf16 v[50:65], v[34:37], v[86:89], v[50:65]
	v_exp_f32_e32 v34, v6
	v_add_f32_e32 v6, v9, v41
	v_fmac_f32_e32 v6, 0xbf8020c5, v201
	v_mul_f32_e32 v6, 0x3db8aa3b, v6
	v_exp_f32_e32 v35, v6
	ds_read_b128 v[6:9], v1 offset:39936
	v_cvt_pk_bf16_f32 v173, v34, v35
	s_waitcnt lgkmcnt(1)
	v_mfma_f32_32x32x16_bf16 v[18:33], v[2:5], v[90:93], v[18:33]
	v_add_f32_e32 v2, v38, v170
	v_add_f32_e32 v2, v39, v2
	v_add_f32_e32 v2, v34, v2
	v_add_f32_e32 v36, v35, v2
	ds_read_b128 v[2:5], v1 offset:40960
	v_cvt_pk_bf16_f32 v170, v199, v200
	s_waitcnt lgkmcnt(1)
	v_mfma_f32_32x32x16_bf16 v[50:65], v[6:9], v[94:97], v[50:65]
	v_mul_f32_e32 v6, 0x3db8aa3b, v10
	v_exp_f32_e32 v10, v6
	v_add_f32_e32 v6, v11, v43
	v_fmac_f32_e32 v6, 0xbf8020c5, v201
	v_mul_f32_e32 v6, 0x3db8aa3b, v6
	v_exp_f32_e32 v11, v6
	ds_read_b128 v[6:9], v1 offset:41984
	s_waitcnt lgkmcnt(1)
	v_mfma_f32_32x32x16_bf16 v[18:33], v[2:5], v[98:101], v[18:33]
	v_add_f32_e32 v2, v10, v36
	v_add_f32_e32 v36, v11, v2
	v_add_f32_e32 v2, v12, v44
	v_fmac_f32_e32 v2, 0xbf8020c5, v201
	v_mul_f32_e32 v2, 0x3db8aa3b, v2
	v_exp_f32_e32 v40, v2
	ds_read_b128 v[2:5], v1 offset:43008
	s_waitcnt lgkmcnt(1)
	v_mfma_f32_32x32x16_bf16 v[50:65], v[6:9], v[102:105], v[50:65]
	v_add_f32_e32 v6, v13, v45
	v_fmac_f32_e32 v6, 0xbf8020c5, v201
	v_mul_f32_e32 v6, 0x3db8aa3b, v6
	v_add_f32_e32 v12, v14, v46
	v_exp_f32_e32 v41, v6
	v_fmac_f32_e32 v12, 0xbf8020c5, v201
	ds_read_b128 v[6:9], v1 offset:44032
	s_waitcnt lgkmcnt(1)
	v_mfma_f32_32x32x16_bf16 v[18:33], v[2:5], v[106:109], v[18:33]
	v_mul_f32_e32 v2, 0x3db8aa3b, v12
	v_exp_f32_e32 v42, v2
	v_add_f32_e32 v2, v15, v47
	v_fmac_f32_e32 v2, 0xbf8020c5, v201
	v_mul_f32_e32 v2, 0x3db8aa3b, v2
	v_exp_f32_e32 v43, v2
	ds_read_b128 v[2:5], v1 offset:45056
	s_waitcnt lgkmcnt(1)
	v_mfma_f32_32x32x16_bf16 v[50:65], v[6:9], v[110:113], v[50:65]
	v_add_f32_e32 v6, v40, v36
	v_add_f32_e32 v6, v41, v6
	v_add_f32_e32 v6, v42, v6
	v_add_f32_e32 v12, v43, v6
	v_add_f32_e32 v13, v16, v48
	ds_read_b128 v[6:9], v1 offset:46080
	v_fmac_f32_e32 v13, 0xbf8020c5, v201
	s_waitcnt lgkmcnt(1)
	v_mfma_f32_32x32x16_bf16 v[18:33], v[2:5], v[114:117], v[18:33]
	v_mul_f32_e32 v2, 0x3db8aa3b, v13
	v_exp_f32_e32 v177, v2
	v_add_f32_e32 v2, v17, v49
	v_fmac_f32_e32 v2, 0xbf8020c5, v201
	v_mul_f32_e32 v2, 0x3db8aa3b, v2
	v_exp_f32_e32 v202, v2
	ds_read_b128 v[2:5], v1 offset:47104
	s_waitcnt lgkmcnt(1)
	v_mfma_f32_32x32x16_bf16 v[50:65], v[6:9], v[118:121], v[50:65]
	v_add_f32_e32 v6, v177, v12
	v_add_f32_e32 v203, v202, v6
	ds_read_b128 v[6:9], v1 offset:48128
	s_waitcnt vmcnt(4)
	s_barrier
	v_cvt_pk_bf16_f32 v174, v10, v11
	v_cvt_pk_bf16_f32 v175, v40, v41
	s_waitcnt lgkmcnt(1)
	v_mfma_f32_32x32x16_bf16 v[18:33], v[2:5], v[126:129], v[18:33]
	v_lshl_add_u64 v[2:3], s[0:1], 0, v[190:191]
	global_load_lds_dwordx4 v[2:3], off
	ds_read_b128 v[2:5], v1 offset:49152
	v_cvt_pk_bf16_f32 v176, v42, v43
	v_cvt_pk_bf16_f32 v177, v177, v202
	s_waitcnt lgkmcnt(1)
	v_mfma_f32_32x32x16_bf16 v[50:65], v[6:9], v[130:133], v[50:65]
	v_lshl_add_u64 v[6:7], s[0:1], 0, v[192:193]
	v_readfirstlane_b32 s0, v198
	s_mov_b32 m0, s0
	s_nop 0
	global_load_lds_dwordx4 v[6:7], off
	ds_read_b128 v[34:37], v1 offset:50176
	s_waitcnt lgkmcnt(1)
	v_mfma_f32_32x32x16_bf16 v[2:17], v[2:5], v[66:69], 0
	s_nop 3
	v_add_f32_e32 v18, v18, v50
	ds_read_b128 v[66:69], v1 offset:51200
	v_fmac_f32_e32 v18, 0xbf8020c5, v201
	v_mul_f32_e32 v18, 0x3db8aa3b, v18
	v_exp_f32_e32 v197, v18
	v_add_f32_e32 v18, v19, v51
	v_fmac_f32_e32 v18, 0xbf8020c5, v201
	v_mul_f32_e32 v18, 0x3db8aa3b, v18
	v_exp_f32_e32 v199, v18
	v_add_f32_e32 v18, v20, v52
	v_fmac_f32_e32 v18, 0xbf8020c5, v201
	v_mul_f32_e32 v18, 0x3db8aa3b, v18
	s_waitcnt lgkmcnt(1)
	v_mfma_f32_32x32x16_bf16 v[34:49], v[34:37], v[70:73], 0
	ds_read_b128 v[70:73], v1 offset:52224
	v_add_f32_e32 v50, v21, v53
	v_fmac_f32_e32 v50, 0xbf8020c5, v201
	v_add_f32_e32 v22, v22, v54
	v_mul_f32_e32 v50, 0x3db8aa3b, v50
	v_fmac_f32_e32 v22, 0xbf8020c5, v201
	v_mul_f32_e32 v22, 0x3db8aa3b, v22
	s_waitcnt lgkmcnt(1)
	v_mfma_f32_32x32x16_bf16 v[2:17], v[66:69], v[74:77], v[2:17]
	v_exp_f32_e32 v66, v18
	ds_read_b128 v[18:21], v1 offset:53248
	v_exp_f32_e32 v67, v50
	v_add_f32_e32 v198, v203, v197
	v_exp_f32_e32 v54, v22
	ds_read_b128 v[50:53], v1 offset:54272
	v_add_f32_e32 v23, v23, v55
	s_waitcnt lgkmcnt(1)
	v_mfma_f32_32x32x16_bf16 v[2:17], v[18:21], v[82:85], v[2:17]
	v_add_f32_e32 v18, v199, v198
	v_add_f32_e32 v18, v66, v18
	v_add_f32_e32 v18, v67, v18
	v_add_f32_e32 v22, v54, v18
	ds_read_b128 v[18:21], v1 offset:55296
	v_fmac_f32_e32 v23, 0xbf8020c5, v201
	v_mul_f32_e32 v23, 0x3db8aa3b, v23
	v_mfma_f32_32x32x16_bf16 v[34:49], v[70:73], v[78:81], v[34:49]
	v_exp_f32_e32 v55, v23
	v_add_f32_e32 v23, v24, v56
	v_fmac_f32_e32 v23, 0xbf8020c5, v201
	v_mul_f32_e32 v23, 0x3db8aa3b, v23
	v_exp_f32_e32 v56, v23
	v_add_f32_e32 v23, v26, v58
	v_fmac_f32_e32 v23, 0xbf8020c5, v201
	s_waitcnt lgkmcnt(1)
	v_mfma_f32_32x32x16_bf16 v[34:49], v[50:53], v[86:89], v[34:49]
	ds_read_b128 v[50:53], v1 offset:56320
	v_mul_f32_e32 v23, 0x3db8aa3b, v23
	v_exp_f32_e32 v26, v23
	v_add_f32_e32 v22, v55, v22
	v_add_f32_e32 v22, v56, v22
	v_add_f32_e32 v28, v28, v60
	v_fmac_f32_e32 v28, 0xbf8020c5, v201
	s_waitcnt lgkmcnt(1)
	v_mfma_f32_32x32x16_bf16 v[2:17], v[18:21], v[90:93], v[2:17]
	v_add_f32_e32 v18, v25, v57
	v_fmac_f32_e32 v18, 0xbf8020c5, v201
	v_mul_f32_e32 v18, 0x3db8aa3b, v18
	v_exp_f32_e32 v57, v18
	ds_read_b128 v[18:21], v1 offset:57344
	v_add_f32_e32 v32, v32, v64
	v_fmac_f32_e32 v32, 0xbf8020c5, v201
	v_add_f32_e32 v22, v57, v22
	s_waitcnt lgkmcnt(1)
	v_mfma_f32_32x32x16_bf16 v[34:49], v[50:53], v[94:97], v[34:49]
	v_add_f32_e32 v50, v26, v22
	ds_read_b128 v[22:25], v1 offset:58368
	v_cvt_pk_bf16_f32 v51, v66, v67
	v_cvt_pk_bf16_f32 v52, v54, v55
	v_cvt_pk_bf16_f32 v53, v56, v57
	s_waitcnt lgkmcnt(1)
	v_mfma_f32_32x32x16_bf16 v[2:17], v[18:21], v[98:101], v[2:17]
	v_add_f32_e32 v18, v27, v59
	v_fmac_f32_e32 v18, 0xbf8020c5, v201
	v_mul_f32_e32 v18, 0x3db8aa3b, v18
	v_exp_f32_e32 v27, v18
	ds_read_b128 v[18:21], v1 offset:59392
	v_cvt_pk_bf16_f32 v54, v26, v27
	s_waitcnt lgkmcnt(1)
	v_mfma_f32_32x32x16_bf16 v[34:49], v[22:25], v[102:105], v[34:49]
	v_mul_f32_e32 v22, 0x3db8aa3b, v28
	v_exp_f32_e32 v28, v22
	v_add_f32_e32 v22, v29, v61
	v_fmac_f32_e32 v22, 0xbf8020c5, v201
	v_mul_f32_e32 v22, 0x3db8aa3b, v22
	v_exp_f32_e32 v29, v22
	ds_read_b128 v[22:25], v1 offset:60416
	s_waitcnt lgkmcnt(1)
	v_mfma_f32_32x32x16_bf16 v[2:17], v[18:21], v[106:109], v[2:17]
	v_add_f32_e32 v18, v27, v50
	v_add_f32_e32 v18, v28, v18
	v_add_f32_e32 v50, v29, v18
	v_add_f32_e32 v18, v30, v62
	v_fmac_f32_e32 v18, 0xbf8020c5, v201
	v_mul_f32_e32 v30, 0x3db8aa3b, v18
	ds_read_b128 v[18:21], v1 offset:61440
	s_waitcnt lgkmcnt(1)
	v_mfma_f32_32x32x16_bf16 v[34:49], v[22:25], v[110:113], v[34:49]
	v_add_f32_e32 v22, v31, v63
	v_fmac_f32_e32 v22, 0xbf8020c5, v201
	v_mul_f32_e32 v22, 0x3db8aa3b, v22
	v_exp_f32_e32 v31, v22
	ds_read_b128 v[22:25], v1 offset:62464
	v_exp_f32_e32 v30, v30
	v_cvt_pk_bf16_f32 v55, v28, v29
	s_waitcnt lgkmcnt(1)
	v_mfma_f32_32x32x16_bf16 v[2:17], v[18:21], v[114:117], v[2:17]
	v_mul_f32_e32 v18, 0x3db8aa3b, v32
	v_exp_f32_e32 v32, v18
	v_add_f32_e32 v18, v33, v65
	v_fmac_f32_e32 v18, 0xbf8020c5, v201
	v_mul_f32_e32 v33, 0x3db8aa3b, v18
	v_exp_f32_e32 v33, v33
	ds_read_b128 v[18:21], v1 offset:63488
	s_waitcnt lgkmcnt(1)
	v_mfma_f32_32x32x16_bf16 v[34:49], v[22:25], v[118:121], v[34:49]
	v_add_f32_e32 v22, v30, v50
	v_add_f32_e32 v22, v31, v22
	v_add_f32_e32 v22, v32, v22
	v_add_f32_e32 v58, v33, v22
	ds_read_b128 v[22:25], v1 offset:64512
	v_cvt_pk_bf16_f32 v50, v197, v199
	v_cvt_pk_bf16_f32 v56, v30, v31
	s_waitcnt lgkmcnt(1)
	v_mfma_f32_32x32x16_bf16 v[2:17], v[18:21], v[126:129], v[2:17]
	v_cvt_pk_bf16_f32 v57, v32, v33
	s_waitcnt lgkmcnt(0)
	v_mfma_f32_32x32x16_bf16 v[34:49], v[22:25], v[130:133], v[34:49]
	s_nop 11
	v_add_f32_e32 v2, v2, v34
	v_fmac_f32_e32 v2, 0xbf8020c5, v201
	v_add_f32_e32 v3, v3, v35
	v_mul_f32_e32 v2, 0x3db8aa3b, v2
	v_fmac_f32_e32 v3, 0xbf8020c5, v201
	v_add_f32_e32 v4, v4, v36
	v_exp_f32_e32 v2, v2
	v_mul_f32_e32 v3, 0x3db8aa3b, v3
	v_fmac_f32_e32 v4, 0xbf8020c5, v201
	v_add_f32_e32 v5, v5, v37
	v_exp_f32_e32 v3, v3
	v_mul_f32_e32 v4, 0x3db8aa3b, v4
	v_fmac_f32_e32 v5, 0xbf8020c5, v201
	v_add_f32_e32 v6, v6, v38
	v_exp_f32_e32 v4, v4
	v_mul_f32_e32 v5, 0x3db8aa3b, v5
	v_fmac_f32_e32 v6, 0xbf8020c5, v201
	v_add_f32_e32 v7, v7, v39
	v_exp_f32_e32 v5, v5
	v_mul_f32_e32 v6, 0x3db8aa3b, v6
	v_fmac_f32_e32 v7, 0xbf8020c5, v201
	v_add_f32_e32 v8, v8, v40
	v_add_f32_e32 v18, v58, v2
	v_exp_f32_e32 v6, v6
	v_mul_f32_e32 v7, 0x3db8aa3b, v7
	v_fmac_f32_e32 v8, 0xbf8020c5, v201
	v_add_f32_e32 v9, v9, v41
	v_add_f32_e32 v18, v3, v18
	v_exp_f32_e32 v7, v7
	v_mul_f32_e32 v8, 0x3db8aa3b, v8
	v_fmac_f32_e32 v9, 0xbf8020c5, v201
	v_add_f32_e32 v10, v10, v42
	v_add_f32_e32 v18, v4, v18
	v_exp_f32_e32 v8, v8
	v_mul_f32_e32 v9, 0x3db8aa3b, v9
	v_fmac_f32_e32 v10, 0xbf8020c5, v201
	v_add_f32_e32 v11, v11, v43
	v_add_f32_e32 v18, v5, v18
	v_exp_f32_e32 v9, v9
	v_mul_f32_e32 v10, 0x3db8aa3b, v10
	v_fmac_f32_e32 v11, 0xbf8020c5, v201
	v_add_f32_e32 v12, v12, v44
	v_add_f32_e32 v18, v6, v18
	v_exp_f32_e32 v10, v10
	v_mul_f32_e32 v11, 0x3db8aa3b, v11
	v_fmac_f32_e32 v12, 0xbf8020c5, v201
	v_add_f32_e32 v13, v13, v45
	v_add_f32_e32 v18, v7, v18
	v_exp_f32_e32 v11, v11
	v_mul_f32_e32 v12, 0x3db8aa3b, v12
	v_fmac_f32_e32 v13, 0xbf8020c5, v201
	v_add_f32_e32 v14, v14, v46
	v_add_f32_e32 v18, v8, v18
	v_exp_f32_e32 v12, v12
	v_mul_f32_e32 v13, 0x3db8aa3b, v13
	v_fmac_f32_e32 v14, 0xbf8020c5, v201
	v_add_f32_e32 v15, v15, v47
	v_add_f32_e32 v18, v9, v18
	v_exp_f32_e32 v13, v13
	v_mul_f32_e32 v14, 0x3db8aa3b, v14
	v_fmac_f32_e32 v15, 0xbf8020c5, v201
	v_add_f32_e32 v16, v16, v48
	v_add_f32_e32 v18, v10, v18
	v_exp_f32_e32 v14, v14
	v_mul_f32_e32 v15, 0x3db8aa3b, v15
	v_fmac_f32_e32 v16, 0xbf8020c5, v201
	v_add_f32_e32 v17, v17, v49
	v_add_f32_e32 v18, v11, v18
	v_exp_f32_e32 v15, v15
	v_mul_f32_e32 v16, 0x3db8aa3b, v16
	v_fmac_f32_e32 v17, 0xbf8020c5, v201
	v_add_f32_e32 v18, v12, v18
	v_exp_f32_e32 v16, v16
	v_mul_f32_e32 v17, 0x3db8aa3b, v17
	v_add_f32_e32 v18, v13, v18
	v_exp_f32_e32 v17, v17
	v_add_f32_e32 v18, v14, v18
	v_add_f32_e32 v18, v15, v18
	v_add_f32_e32 v18, v16, v18
	v_add_f32_e32 v18, v17, v18
	v_cvt_pk_bf16_f32 v34, v2, v3
	ds_bpermute_b32 v2, v189, v18
	v_cvt_pk_bf16_f32 v35, v4, v5
	v_cvt_pk_bf16_f32 v36, v6, v7
	v_cvt_pk_bf16_f32 v37, v8, v9
	v_cvt_pk_bf16_f32 v38, v10, v11
	s_waitcnt lgkmcnt(0)
	v_add_f32_e32 v2, v18, v2
	v_div_scale_f32 v3, s[0:1], v2, v2, 1.0
	v_rcp_f32_e32 v4, v3
	s_add_u32 s0, s28, s22
	s_addc_u32 s1, s29, s23
	v_cvt_pk_bf16_f32 v39, v12, v13
	v_fma_f32 v5, -v3, v4, 1.0
	v_fmac_f32_e32 v4, v5, v4
	v_div_scale_f32 v5, vcc, 1.0, v2, 1.0
	v_mul_f32_e32 v6, v5, v4
	v_fma_f32 v7, -v3, v6, v5
	v_fmac_f32_e32 v6, v7, v4
	v_fma_f32 v3, -v3, v6, v5
	v_div_fmas_f32 v3, v3, v4, v6
	v_div_fixup_f32 v42, v3, v2, 1.0
	v_lshl_add_u64 v[2:3], s[0:1], 0, v[194:195]
	v_cvt_pk_bf16_f32 v40, v14, v15
	v_cvt_pk_bf16_f32 v41, v16, v17
	v_mov_b32_e32 v43, v42
	v_lshl_add_u64 v[44:45], v[182:183], 0, s[38:39]
	v_lshl_add_u64 v[46:47], v[184:185], 0, s[38:39]
	v_lshl_add_u64 v[48:49], v[186:187], 0, v[2:3]
	s_mov_b64 s[22:23], 0
	s_branch .LBB0_249
.LBB0_248:
	s_and_b32 s0, s22, 0xc000
	v_add_u32_e32 v62, s0, v1
	ds_read_b128 v[2:5], v62
	ds_read_b128 v[18:21], v62 offset:1024
	ds_read_b128 v[58:61], v62 offset:2048
	ds_read_b128 v[64:67], v62 offset:3072
	ds_read_b128 v[68:71], v62 offset:4096
	ds_read_b128 v[72:75], v62 offset:5120
	s_add_i32 s16, s16, 1
	s_add_u32 s22, s22, 0x4000
	s_addc_u32 s23, s23, 0
	s_cmp_lg_u32 s22, 0x20000
	s_waitcnt lgkmcnt(5)
	v_mfma_f32_32x32x16_bf16 v[2:17], v[2:5], v[122:125], 0
	s_waitcnt lgkmcnt(3)
	v_mfma_f32_32x32x16_bf16 v[2:17], v[58:61], v[138:141], v[2:17]
	ds_read_b128 v[58:61], v62 offset:6144
	v_mfma_f32_32x32x16_bf16 v[18:33], v[18:21], v[134:137], 0
	s_waitcnt lgkmcnt(3)
	v_mfma_f32_32x32x16_bf16 v[18:33], v[64:67], v[142:145], v[18:33]
	ds_read_b128 v[64:67], v62 offset:7168
	s_waitcnt lgkmcnt(3)
	v_mfma_f32_32x32x16_bf16 v[2:17], v[68:71], v[146:149], v[2:17]
	ds_read_b128 v[68:71], v62 offset:8192
	s_waitcnt lgkmcnt(3)
	v_mfma_f32_32x32x16_bf16 v[18:33], v[72:75], v[150:153], v[18:33]
	ds_read_b128 v[72:75], v62 offset:9216
	s_waitcnt lgkmcnt(3)
	v_mfma_f32_32x32x16_bf16 v[2:17], v[58:61], v[154:157], v[2:17]
	ds_read_b128 v[58:61], v62 offset:10240
	s_waitcnt lgkmcnt(3)
	v_mfma_f32_32x32x16_bf16 v[18:33], v[64:67], v[158:161], v[18:33]
	ds_read_b128 v[64:67], v62 offset:11264
	s_waitcnt lgkmcnt(3)
	v_mfma_f32_32x32x16_bf16 v[2:17], v[68:71], v[162:165], v[2:17]
	ds_read_b128 v[68:71], v62 offset:12288
	s_waitcnt lgkmcnt(3)
	v_mfma_f32_32x32x16_bf16 v[18:33], v[72:75], v[166:169], v[18:33]
	ds_read_b128 v[72:75], v62 offset:13312
	s_waitcnt lgkmcnt(3)
	v_mfma_f32_32x32x16_bf16 v[2:17], v[58:61], v[170:173], v[2:17]
	ds_read_b128 v[58:61], v62 offset:14336
	s_waitcnt lgkmcnt(3)
	v_mfma_f32_32x32x16_bf16 v[18:33], v[64:67], v[174:177], v[18:33]
	ds_read_b128 v[64:67], v62 offset:15360
	s_waitcnt lgkmcnt(3)
	v_mfma_f32_32x32x16_bf16 v[2:17], v[68:71], v[50:53], v[2:17]
	s_waitcnt lgkmcnt(2)
	v_mfma_f32_32x32x16_bf16 v[18:33], v[72:75], v[54:57], v[18:33]
	s_waitcnt lgkmcnt(1)
	v_mfma_f32_32x32x16_bf16 v[2:17], v[58:61], v[34:37], v[2:17]
	s_waitcnt lgkmcnt(0)
	v_mfma_f32_32x32x16_bf16 v[18:33], v[64:67], v[38:41], v[18:33]
	s_nop 11
	v_pk_add_f32 v[4:5], v[4:5], v[20:21]
	v_pk_add_f32 v[2:3], v[2:3], v[18:19]
	v_pk_mul_f32 v[4:5], v[42:43], v[4:5]
	v_pk_mul_f32 v[2:3], v[42:43], v[2:3]
	v_pk_add_f32 v[8:9], v[8:9], v[24:25]
	v_pk_add_f32 v[6:7], v[6:7], v[22:23]
	v_cvt_pk_bf16_f32 v2, v2, v3
	v_cvt_pk_bf16_f32 v3, v4, v5
	global_store_dwordx2 v[48:49], v[2:3], off offset:-32
	v_pk_mul_f32 v[2:3], v[42:43], v[6:7]
	v_pk_mul_f32 v[4:5], v[42:43], v[8:9]
	v_pk_add_f32 v[12:13], v[12:13], v[28:29]
	v_pk_add_f32 v[10:11], v[10:11], v[26:27]
	v_cvt_pk_bf16_f32 v2, v2, v3
	v_cvt_pk_bf16_f32 v3, v4, v5
	global_store_dwordx2 v[48:49], v[2:3], off offset:-16
	v_pk_mul_f32 v[2:3], v[42:43], v[10:11]
	v_pk_mul_f32 v[4:5], v[42:43], v[12:13]
	v_pk_add_f32 v[16:17], v[16:17], v[32:33]
	v_pk_add_f32 v[14:15], v[14:15], v[30:31]
	v_cvt_pk_bf16_f32 v2, v2, v3
	v_cvt_pk_bf16_f32 v3, v4, v5
	global_store_dwordx2 v[48:49], v[2:3], off
	v_pk_mul_f32 v[2:3], v[42:43], v[14:15]
	v_pk_mul_f32 v[4:5], v[42:43], v[16:17]
	v_cvt_pk_bf16_f32 v2, v2, v3
	v_cvt_pk_bf16_f32 v3, v4, v5
	global_store_dwordx2 v[48:49], v[2:3], off offset:16
	v_lshl_add_u64 v[48:49], v[48:49], 0, 64
	s_cbranch_scc0 .LBB0_242
